# all four GEMM loops: static prio waves 4-7, priority flips and redundant post-barrier lgkmcnt(0) removed from MFMA segments; loop heads at +4 mod 64
# baseline (speedup 1.0000x reference)
; #define PG8_STAGE(bufoff, gbase, voff) do { _Pragma("unroll") for (int _i = 0; _i < 2; ++_i) \
;         __builtin_amdgcn_global_load_lds((const unsigned*)((const char*)(gbase) + (voff)[_i]), (PG8_LAS unsigned*)(lds + (bufoff) + ldsw + _i * 8192), 16, 0, 0); } while (0)
; #define PG8_LDA(dst, b, h) do { _Pragma("unroll") for (int m = 0; m < 4; ++m) _Pragma("unroll") for (int k = 0; k < 2; ++k) dst[m][k] = *(const PG8_LAS bf16x8*)(lds + PG8_SA(b, h) + aoff + m * 2048 + k * 1024); } while (0)
; #define PG8_LDB(dst, b, h) do { _Pragma("unroll") for (int n = 0; n < 2; ++n) _Pragma("unroll") for (int k = 0; k < 2; ++k) dst[n][k] = *(const PG8_LAS bf16x8*)(lds + PG8_SB(b, h) + boff + n * 2048 + k * 1024); } while (0)
; #define PG8_MMA(ai, bj, At, Bt) do { __builtin_amdgcn_s_setprio(1); _Pragma("unroll") for (int m = 0; m < 4; ++m) _Pragma("unroll") for (int n = 0; n < 2; ++n) _Pragma("unroll") for (int k = 0; k < 2; ++k) \
;         acc[ai][bj][m][n] = __builtin_amdgcn_mfma_f32_16x16x32_bf16(Bt[n][k], At[m][k], acc[ai][bj][m][n], 0, 0, 0); __builtin_amdgcn_s_setprio(0); } while (0)
; #define PG8_WAIT_V(n) asm volatile("s_waitcnt vmcnt(" #n ")" ::: "memory")
; #define PG8_WAIT_L(n) asm volatile("s_waitcnt lgkmcnt(" #n ")" ::: "memory")
; #define PG8_BAR __builtin_amdgcn_s_barrier()
; #define PG8_SCHED __builtin_amdgcn_sched_barrier(0)
; template <class Epi, class Sched, bool ALIGN_EPI = false, bool SP2 = false>
; __device__ __forceinline__ void gemm_phase(PG8_LAS unsigned char* lds, const Gemm g, const Sched& S, const Epi& E) {
;     ...
;             const char* a2 = last ? nA : cA + (size_t)(t + 2) * kstep; const char* b2 = last ? nB : cB + (size_t)(t + 2) * kstep;
;             const char* a3 = a2 + kstep; const char* b3 = b2 + kstep;
;             if (last && has_next) S.a_ready(nxt);
;             if constexpr (SP2) {
;             PG8_LDB(B0, 0, 0); PG8_LDB(B1, 0, 1); PG8_SCHED; PG8_LDA(At, 0, 0); PG8_STAGE(PG8_SA(1, 1), a1 + hstep, voffA);
;             PG8_WAIT_V(8); PG8_WAIT_L(0); PG8_BAR; PG8_MMA(0, 0, At, B0); PG8_MMA(0, 1, At, B1); PG8_BAR; PG8_SCHED;
;             PG8_LDA(At, 0, 1); PG8_STAGE(PG8_SB(0, 0), b2, voffB); PG8_STAGE(PG8_SB(0, 1), b2 + hstep, voffB); PG8_STAGE(PG8_SA(0, 0), a2, voffA);
.Lmy_p1_prio_done:
.LBB0_118:
	s_add_u32 s2, s50, 0xfff80080
	s_addc_u32 s3, s51, -1
	s_add_i32 s58, 0, 0x10000
	s_cmp_eq_u32 s57, 28
	s_cselect_b32 s53, s21, s3
	s_cselect_b32 s52, s24, s2
	s_cselect_b32 s23, s19, s56
	s_cselect_b32 s22, s25, s43
	s_add_i32 s59, 0, 0x14000
	v_add_u32_e32 v156, s58, v149
	v_add_u32_e32 v172, s59, v149
	ds_read_b128 v[140:143], v156
	ds_read_b128 v[144:147], v156 offset:1024
	ds_read_b128 v[152:155], v156 offset:2048
	ds_read_b128 v[156:159], v156 offset:3072
	ds_read_b128 v[160:163], v172
	ds_read_b128 v[164:167], v172 offset:1024
	ds_read_b128 v[168:171], v172 offset:2048
	ds_read_b128 v[172:175], v172 offset:3072
	v_lshl_add_u64 v[184:185], s[50:51], 0, v[138:139]
	s_add_i32 m0, s35, 0xc000
	ds_read_b128 v[176:179], v151
	ds_read_b128 v[180:183], v151 offset:1024
	ds_read_b128 v[200:203], v151 offset:2048
	ds_read_b128 v[204:207], v151 offset:3072
	ds_read_b128 v[208:211], v151 offset:4096
	ds_read_b128 v[212:215], v151 offset:5120
	ds_read_b128 v[216:219], v151 offset:6144
	ds_read_b128 v[232:235], v151 offset:7168
	global_load_lds_dwordx4 v[184:185], off
	v_lshl_add_u64 v[184:185], s[50:51], 0, v[136:137]
	s_add_i32 m0, s35, 0xe000
	s_nop 0
	global_load_lds_dwordx4 v[184:185], off
	s_waitcnt vmcnt(8)
	s_waitcnt lgkmcnt(0)
	s_barrier
	v_mfma_f32_16x16x32_bf16 v[126:129], v[140:143], v[176:179], v[126:129]
	v_mfma_f32_16x16x32_bf16 v[122:125], v[152:155], v[176:179], v[122:125]
	v_mfma_f32_16x16x32_bf16 v[110:113], v[140:143], v[200:203], v[110:113]
	v_mfma_f32_16x16x32_bf16 v[106:109], v[152:155], v[200:203], v[106:109]
	v_mfma_f32_16x16x32_bf16 v[94:97], v[140:143], v[208:211], v[94:97]
	v_mfma_f32_16x16x32_bf16 v[90:93], v[152:155], v[208:211], v[90:93]
	v_mfma_f32_16x16x32_bf16 v[78:81], v[140:143], v[216:219], v[78:81]
	v_mfma_f32_16x16x32_bf16 v[74:77], v[152:155], v[216:219], v[74:77]
	v_mfma_f32_16x16x32_bf16 v[126:129], v[144:147], v[180:183], v[126:129]
	v_mfma_f32_16x16x32_bf16 v[122:125], v[156:159], v[180:183], v[122:125]
	v_mfma_f32_16x16x32_bf16 v[110:113], v[144:147], v[204:207], v[110:113]
	v_mfma_f32_16x16x32_bf16 v[106:109], v[156:159], v[204:207], v[106:109]
	v_mfma_f32_16x16x32_bf16 v[94:97], v[144:147], v[212:215], v[94:97]
	v_mfma_f32_16x16x32_bf16 v[90:93], v[156:159], v[212:215], v[90:93]
	v_mfma_f32_16x16x32_bf16 v[78:81], v[144:147], v[232:235], v[78:81]
	v_mfma_f32_16x16x32_bf16 v[74:77], v[156:159], v[232:235], v[74:77]
	v_mfma_f32_16x16x32_bf16 v[118:121], v[160:163], v[176:179], v[118:121]
	v_mfma_f32_16x16x32_bf16 v[114:117], v[168:171], v[176:179], v[114:117]
	v_mfma_f32_16x16x32_bf16 v[102:105], v[160:163], v[200:203], v[102:105]
	v_mfma_f32_16x16x32_bf16 v[98:101], v[168:171], v[200:203], v[98:101]
	v_mfma_f32_16x16x32_bf16 v[86:89], v[160:163], v[208:211], v[86:89]
	v_mfma_f32_16x16x32_bf16 v[82:85], v[168:171], v[208:211], v[82:85]
	v_mfma_f32_16x16x32_bf16 v[70:73], v[160:163], v[216:219], v[70:73]
	v_mfma_f32_16x16x32_bf16 v[66:69], v[168:171], v[216:219], v[66:69]
	v_mfma_f32_16x16x32_bf16 v[118:121], v[164:167], v[180:183], v[118:121]
	v_mfma_f32_16x16x32_bf16 v[114:117], v[172:175], v[180:183], v[114:117]
	v_mfma_f32_16x16x32_bf16 v[102:105], v[164:167], v[204:207], v[102:105]
	v_mfma_f32_16x16x32_bf16 v[98:101], v[172:175], v[204:207], v[98:101]
	v_mfma_f32_16x16x32_bf16 v[86:89], v[164:167], v[212:215], v[86:89]
	v_mfma_f32_16x16x32_bf16 v[82:85], v[172:175], v[212:215], v[82:85]
	v_mfma_f32_16x16x32_bf16 v[70:73], v[164:167], v[232:235], v[70:73]
	v_mfma_f32_16x16x32_bf16 v[66:69], v[172:175], v[232:235], v[66:69]
	s_barrier
	s_add_i32 s2, s58, s33
	v_lshl_add_u64 v[184:185], s[22:23], 0, v[0:1]
	s_mov_b32 m0, s2
	ds_read_b128 v[176:179], v151 offset:16384
	ds_read_b128 v[180:183], v151 offset:17408
	ds_read_b128 v[200:203], v151 offset:18432
	ds_read_b128 v[204:207], v151 offset:19456
	ds_read_b128 v[208:211], v151 offset:20480
	ds_read_b128 v[212:215], v151 offset:21504
	ds_read_b128 v[216:219], v151 offset:22528
	ds_read_b128 v[232:235], v151 offset:23552
	global_load_lds_dwordx4 v[184:185], off
	s_add_i32 m0, s2, 0x2000
	s_add_u32 s2, s22, 0x80000
	v_lshl_add_u64 v[236:237], s[22:23], 0, v[134:135]
	s_addc_u32 s3, s23, 0
	s_add_i32 s58, s59, s33
	global_load_lds_dwordx4 v[236:237], off
	v_lshl_add_u64 v[238:239], s[2:3], 0, v[0:1]
	s_mov_b32 m0, s58
	v_lshl_add_u64 v[240:241], s[52:53], 0, v[132:133]
	global_load_lds_dwordx4 v[238:239], off
	v_lshl_add_u64 v[238:239], s[2:3], 0, v[134:135]
	s_add_i32 m0, s58, 0x2000
	s_nop 0
	global_load_lds_dwordx4 v[238:239], off
	v_lshl_add_u64 v[238:239], s[52:53], 0, v[130:131]
	s_mov_b32 m0, s35
	s_nop 0
	global_load_lds_dwordx4 v[238:239], off
	s_mov_b32 m0, s36
	s_nop 0
	global_load_lds_dwordx4 v[240:241], off
	s_waitcnt vmcnt(8)
	s_waitcnt lgkmcnt(0)
	s_barrier
; #define PG8_STAGE(bufoff, gbase, voff) do { _Pragma("unroll") for (int _i = 0; _i < 2; ++_i) \
;         __builtin_amdgcn_global_load_lds((const unsigned*)((const char*)(gbase) + (voff)[_i]), (PG8_LAS unsigned*)(lds + (bufoff) + ldsw + _i * 8192), 16, 0, 0); } while (0)
; #define PG8_LDA(dst, b, h) do { _Pragma("unroll") for (int m = 0; m < 4; ++m) _Pragma("unroll") for (int k = 0; k < 2; ++k) dst[m][k] = *(const PG8_LAS bf16x8*)(lds + PG8_SA(b, h) + aoff + m * 2048 + k * 1024); } while (0)
; #define PG8_LDB(dst, b, h) do { _Pragma("unroll") for (int n = 0; n < 2; ++n) _Pragma("unroll") for (int k = 0; k < 2; ++k) dst[n][k] = *(const PG8_LAS bf16x8*)(lds + PG8_SB(b, h) + boff + n * 2048 + k * 1024); } while (0)
; #define PG8_MMA(ai, bj, At, Bt) do { __builtin_amdgcn_s_setprio(1); _Pragma("unroll") for (int m = 0; m < 4; ++m) _Pragma("unroll") for (int n = 0; n < 2; ++n) _Pragma("unroll") for (int k = 0; k < 2; ++k) \
;         acc[ai][bj][m][n] = __builtin_amdgcn_mfma_f32_16x16x32_bf16(Bt[n][k], At[m][k], acc[ai][bj][m][n], 0, 0, 0); __builtin_amdgcn_s_setprio(0); } while (0)
; #define PG8_WAIT_V(n) asm volatile("s_waitcnt vmcnt(" #n ")" ::: "memory")
; #define PG8_WAIT_L(n) asm volatile("s_waitcnt lgkmcnt(" #n ")" ::: "memory")
; #define PG8_BAR __builtin_amdgcn_s_barrier()
; #define PG8_SCHED __builtin_amdgcn_sched_barrier(0)
; template <class Epi, class Sched, bool ALIGN_EPI = false, bool SP2 = false>
; __device__ __forceinline__ void gemm_phase(PG8_LAS unsigned char* lds, const Gemm g, const Sched& S, const Epi& E) {
;     ...
;             PG8_WAIT_V(8); PG8_WAIT_L(0); PG8_BAR; PG8_MMA(1, 0, At, B0); PG8_MMA(1, 1, At, B1); PG8_BAR; PG8_SCHED;
;             PG8_LDB(B0, 1, 0); PG8_LDB(B1, 1, 1); PG8_SCHED; PG8_LDA(At, 1, 0); PG8_STAGE(PG8_SA(0, 1), a2 + hstep, voffA);
;             PG8_WAIT_V(8); PG8_WAIT_L(0); PG8_BAR; PG8_MMA(0, 0, At, B0); PG8_MMA(0, 1, At, B1); PG8_BAR; PG8_SCHED;
	v_mfma_f32_16x16x32_bf16 v[62:65], v[140:143], v[176:179], v[62:65]
	v_mfma_f32_16x16x32_bf16 v[58:61], v[152:155], v[176:179], v[58:61]
	v_mfma_f32_16x16x32_bf16 v[46:49], v[140:143], v[200:203], v[46:49]
	v_mfma_f32_16x16x32_bf16 v[42:45], v[152:155], v[200:203], v[42:45]
	v_mfma_f32_16x16x32_bf16 v[30:33], v[140:143], v[208:211], v[30:33]
	v_mfma_f32_16x16x32_bf16 v[26:29], v[152:155], v[208:211], v[26:29]
	v_mfma_f32_16x16x32_bf16 v[14:17], v[140:143], v[216:219], v[14:17]
	v_mfma_f32_16x16x32_bf16 v[10:13], v[152:155], v[216:219], v[10:13]
	v_mfma_f32_16x16x32_bf16 v[62:65], v[144:147], v[180:183], v[62:65]
	v_mfma_f32_16x16x32_bf16 v[58:61], v[156:159], v[180:183], v[58:61]
	v_mfma_f32_16x16x32_bf16 v[46:49], v[144:147], v[204:207], v[46:49]
	v_mfma_f32_16x16x32_bf16 v[42:45], v[156:159], v[204:207], v[42:45]
	v_mfma_f32_16x16x32_bf16 v[30:33], v[144:147], v[212:215], v[30:33]
	v_mfma_f32_16x16x32_bf16 v[26:29], v[156:159], v[212:215], v[26:29]
	v_mfma_f32_16x16x32_bf16 v[14:17], v[144:147], v[232:235], v[14:17]
	v_mfma_f32_16x16x32_bf16 v[10:13], v[156:159], v[232:235], v[10:13]
	v_mfma_f32_16x16x32_bf16 v[54:57], v[160:163], v[176:179], v[54:57]
	v_mfma_f32_16x16x32_bf16 v[50:53], v[168:171], v[176:179], v[50:53]
	v_mfma_f32_16x16x32_bf16 v[38:41], v[160:163], v[200:203], v[38:41]
	v_mfma_f32_16x16x32_bf16 v[34:37], v[168:171], v[200:203], v[34:37]
	v_mfma_f32_16x16x32_bf16 v[22:25], v[160:163], v[208:211], v[22:25]
	v_mfma_f32_16x16x32_bf16 v[18:21], v[168:171], v[208:211], v[18:21]
	v_mfma_f32_16x16x32_bf16 v[6:9], v[160:163], v[216:219], v[6:9]
	v_mfma_f32_16x16x32_bf16 v[2:5], v[168:171], v[216:219], v[2:5]
	v_mfma_f32_16x16x32_bf16 v[54:57], v[164:167], v[180:183], v[54:57]
	v_mfma_f32_16x16x32_bf16 v[50:53], v[172:175], v[180:183], v[50:53]
	v_mfma_f32_16x16x32_bf16 v[38:41], v[164:167], v[204:207], v[38:41]
	v_mfma_f32_16x16x32_bf16 v[34:37], v[172:175], v[204:207], v[34:37]
	v_mfma_f32_16x16x32_bf16 v[22:25], v[164:167], v[212:215], v[22:25]
	v_mfma_f32_16x16x32_bf16 v[18:21], v[172:175], v[212:215], v[18:21]
	v_mfma_f32_16x16x32_bf16 v[6:9], v[164:167], v[232:235], v[6:9]
	v_mfma_f32_16x16x32_bf16 v[2:5], v[172:175], v[232:235], v[2:5]
	s_barrier
	s_add_i32 s58, 0, 0x18000
	s_add_i32 s59, 0, 0x1c000
	v_add_u32_e32 v156, s58, v149
	v_add_u32_e32 v172, s59, v149
	ds_read_b128 v[140:143], v156
	ds_read_b128 v[144:147], v156 offset:1024
	ds_read_b128 v[152:155], v156 offset:2048
	ds_read_b128 v[156:159], v156 offset:3072
	ds_read_b128 v[160:163], v172
	ds_read_b128 v[164:167], v172 offset:1024
	ds_read_b128 v[168:171], v172 offset:2048
	ds_read_b128 v[172:175], v172 offset:3072
	s_add_u32 s2, s52, 0x80000
	s_addc_u32 s3, s53, 0
	s_mov_b32 m0, s37
	v_lshl_add_u64 v[242:243], s[2:3], 0, v[130:131]
	ds_read_b128 v[176:179], v151 offset:32768
	ds_read_b128 v[180:183], v151 offset:33792
	ds_read_b128 v[200:203], v151 offset:34816
	ds_read_b128 v[204:207], v151 offset:35840
	ds_read_b128 v[208:211], v151 offset:36864
	ds_read_b128 v[212:215], v151 offset:37888
	ds_read_b128 v[216:219], v151 offset:38912
	ds_read_b128 v[232:235], v151 offset:39936
	global_load_lds_dwordx4 v[242:243], off
	v_lshl_add_u64 v[242:243], s[2:3], 0, v[132:133]
	s_mov_b32 m0, s38
	s_nop 0
	global_load_lds_dwordx4 v[242:243], off
	s_waitcnt vmcnt(8)
	s_waitcnt lgkmcnt(0)
	s_barrier
	v_mfma_f32_16x16x32_bf16 v[126:129], v[140:143], v[176:179], v[126:129]
	v_mfma_f32_16x16x32_bf16 v[122:125], v[152:155], v[176:179], v[122:125]
	v_mfma_f32_16x16x32_bf16 v[110:113], v[140:143], v[200:203], v[110:113]
	v_mfma_f32_16x16x32_bf16 v[106:109], v[152:155], v[200:203], v[106:109]
	v_mfma_f32_16x16x32_bf16 v[94:97], v[140:143], v[208:211], v[94:97]
	v_mfma_f32_16x16x32_bf16 v[90:93], v[152:155], v[208:211], v[90:93]
	v_mfma_f32_16x16x32_bf16 v[78:81], v[140:143], v[216:219], v[78:81]
	v_mfma_f32_16x16x32_bf16 v[74:77], v[152:155], v[216:219], v[74:77]
	v_mfma_f32_16x16x32_bf16 v[126:129], v[144:147], v[180:183], v[126:129]
	v_mfma_f32_16x16x32_bf16 v[122:125], v[156:159], v[180:183], v[122:125]
	v_mfma_f32_16x16x32_bf16 v[110:113], v[144:147], v[204:207], v[110:113]
	v_mfma_f32_16x16x32_bf16 v[106:109], v[156:159], v[204:207], v[106:109]
	v_mfma_f32_16x16x32_bf16 v[94:97], v[144:147], v[212:215], v[94:97]
	v_mfma_f32_16x16x32_bf16 v[90:93], v[156:159], v[212:215], v[90:93]
	v_mfma_f32_16x16x32_bf16 v[78:81], v[144:147], v[232:235], v[78:81]
	v_mfma_f32_16x16x32_bf16 v[74:77], v[156:159], v[232:235], v[74:77]
	v_mfma_f32_16x16x32_bf16 v[118:121], v[160:163], v[176:179], v[118:121]
	v_mfma_f32_16x16x32_bf16 v[114:117], v[168:171], v[176:179], v[114:117]
	v_mfma_f32_16x16x32_bf16 v[102:105], v[160:163], v[200:203], v[102:105]
	v_mfma_f32_16x16x32_bf16 v[98:101], v[168:171], v[200:203], v[98:101]
	v_mfma_f32_16x16x32_bf16 v[86:89], v[160:163], v[208:211], v[86:89]
	v_mfma_f32_16x16x32_bf16 v[82:85], v[168:171], v[208:211], v[82:85]
	v_mfma_f32_16x16x32_bf16 v[70:73], v[160:163], v[216:219], v[70:73]
	v_mfma_f32_16x16x32_bf16 v[66:69], v[168:171], v[216:219], v[66:69]
	v_mfma_f32_16x16x32_bf16 v[118:121], v[164:167], v[180:183], v[118:121]
	v_mfma_f32_16x16x32_bf16 v[114:117], v[172:175], v[180:183], v[114:117]
	v_mfma_f32_16x16x32_bf16 v[102:105], v[164:167], v[204:207], v[102:105]
	v_mfma_f32_16x16x32_bf16 v[98:101], v[172:175], v[204:207], v[98:101]
	v_mfma_f32_16x16x32_bf16 v[86:89], v[164:167], v[212:215], v[86:89]
	v_mfma_f32_16x16x32_bf16 v[82:85], v[172:175], v[212:215], v[82:85]
	v_mfma_f32_16x16x32_bf16 v[70:73], v[164:167], v[232:235], v[70:73]
	v_mfma_f32_16x16x32_bf16 v[66:69], v[172:175], v[232:235], v[66:69]
	s_barrier
; #define PG8_STAGE(bufoff, gbase, voff) do { _Pragma("unroll") for (int _i = 0; _i < 2; ++_i) \
;         __builtin_amdgcn_global_load_lds((const unsigned*)((const char*)(gbase) + (voff)[_i]), (PG8_LAS unsigned*)(lds + (bufoff) + ldsw + _i * 8192), 16, 0, 0); } while (0)
; #define PG8_LDA(dst, b, h) do { _Pragma("unroll") for (int m = 0; m < 4; ++m) _Pragma("unroll") for (int k = 0; k < 2; ++k) dst[m][k] = *(const PG8_LAS bf16x8*)(lds + PG8_SA(b, h) + aoff + m * 2048 + k * 1024); } while (0)
; #define PG8_MMA(ai, bj, At, Bt) do { __builtin_amdgcn_s_setprio(1); _Pragma("unroll") for (int m = 0; m < 4; ++m) _Pragma("unroll") for (int n = 0; n < 2; ++n) _Pragma("unroll") for (int k = 0; k < 2; ++k) \
;         acc[ai][bj][m][n] = __builtin_amdgcn_mfma_f32_16x16x32_bf16(Bt[n][k], At[m][k], acc[ai][bj][m][n], 0, 0, 0); __builtin_amdgcn_s_setprio(0); } while (0)
; #define PG8_WAIT_V(n) asm volatile("s_waitcnt vmcnt(" #n ")" ::: "memory")
; #define PG8_WAIT_L(n) asm volatile("s_waitcnt lgkmcnt(" #n ")" ::: "memory")
; #define PG8_BAR __builtin_amdgcn_s_barrier()
; #define PG8_SCHED __builtin_amdgcn_sched_barrier(0)
; template <class Epi, class Sched, bool ALIGN_EPI = false, bool SP2 = false>
; __device__ __forceinline__ void gemm_phase(PG8_LAS unsigned char* lds, const Gemm g, const Sched& S, const Epi& E) {
;     ...
;             PG8_LDA(At, 1, 1); PG8_STAGE(PG8_SB(1, 0), b3, voffB); PG8_STAGE(PG8_SB(1, 1), b3 + hstep, voffB); PG8_STAGE(PG8_SA(1, 0), a3, voffA);
;             PG8_WAIT_V(8); PG8_WAIT_L(0); PG8_BAR; PG8_MMA(1, 0, At, B0); PG8_MMA(1, 1, At, B1); PG8_BAR; PG8_SCHED;
;     ...
;         }
;         if constexpr (ALIGN_EPI) { if (wr == 0) PG8_BAR; }
	s_add_i32 s2, s58, s33
	v_lshl_add_u64 v[184:185], v[184:185], 0, s[0:1]
	s_mov_b32 m0, s2
	ds_read_b128 v[176:179], v151 offset:49152
	ds_read_b128 v[180:183], v151 offset:50176
	ds_read_b128 v[200:203], v151 offset:51200
	ds_read_b128 v[204:207], v151 offset:52224
	ds_read_b128 v[208:211], v151 offset:53248
	ds_read_b128 v[212:215], v151 offset:54272
	ds_read_b128 v[216:219], v151 offset:55296
	ds_read_b128 v[232:235], v151 offset:56320
	global_load_lds_dwordx4 v[184:185], off
	s_add_i32 m0, s2, 0x2000
	s_add_u32 s2, s22, 0x80080
	v_lshl_add_u64 v[184:185], v[236:237], 0, s[0:1]
	s_addc_u32 s3, s23, 0
	s_add_i32 s22, s59, s33
	global_load_lds_dwordx4 v[184:185], off
	v_lshl_add_u64 v[184:185], s[2:3], 0, v[0:1]
	s_mov_b32 m0, s22
	s_nop 0
	global_load_lds_dwordx4 v[184:185], off
	v_lshl_add_u64 v[184:185], s[2:3], 0, v[134:135]
	s_add_i32 m0, s22, 0x2000
	s_nop 0
	global_load_lds_dwordx4 v[184:185], off
	v_lshl_add_u64 v[184:185], v[238:239], 0, s[0:1]
	s_mov_b32 m0, s49
	s_nop 0
	global_load_lds_dwordx4 v[184:185], off
	v_lshl_add_u64 v[184:185], v[240:241], 0, s[0:1]
	s_mov_b32 m0, s54
	s_nop 0
	global_load_lds_dwordx4 v[184:185], off
	s_waitcnt vmcnt(8)
	s_waitcnt lgkmcnt(0)
	s_barrier
	v_mfma_f32_16x16x32_bf16 v[62:65], v[140:143], v[176:179], v[62:65]
	v_mfma_f32_16x16x32_bf16 v[58:61], v[152:155], v[176:179], v[58:61]
	v_mfma_f32_16x16x32_bf16 v[46:49], v[140:143], v[200:203], v[46:49]
	v_mfma_f32_16x16x32_bf16 v[42:45], v[152:155], v[200:203], v[42:45]
	v_mfma_f32_16x16x32_bf16 v[30:33], v[140:143], v[208:211], v[30:33]
	v_mfma_f32_16x16x32_bf16 v[26:29], v[152:155], v[208:211], v[26:29]
	v_mfma_f32_16x16x32_bf16 v[14:17], v[140:143], v[216:219], v[14:17]
	v_mfma_f32_16x16x32_bf16 v[10:13], v[152:155], v[216:219], v[10:13]
	v_mfma_f32_16x16x32_bf16 v[62:65], v[144:147], v[180:183], v[62:65]
	v_mfma_f32_16x16x32_bf16 v[58:61], v[156:159], v[180:183], v[58:61]
	v_mfma_f32_16x16x32_bf16 v[46:49], v[144:147], v[204:207], v[46:49]
	v_mfma_f32_16x16x32_bf16 v[42:45], v[156:159], v[204:207], v[42:45]
	v_mfma_f32_16x16x32_bf16 v[30:33], v[144:147], v[212:215], v[30:33]
	v_mfma_f32_16x16x32_bf16 v[26:29], v[156:159], v[212:215], v[26:29]
	v_mfma_f32_16x16x32_bf16 v[14:17], v[144:147], v[232:235], v[14:17]
	v_mfma_f32_16x16x32_bf16 v[10:13], v[156:159], v[232:235], v[10:13]
	v_mfma_f32_16x16x32_bf16 v[54:57], v[160:163], v[176:179], v[54:57]
	v_mfma_f32_16x16x32_bf16 v[50:53], v[168:171], v[176:179], v[50:53]
	v_mfma_f32_16x16x32_bf16 v[38:41], v[160:163], v[200:203], v[38:41]
	v_mfma_f32_16x16x32_bf16 v[34:37], v[168:171], v[200:203], v[34:37]
	v_mfma_f32_16x16x32_bf16 v[22:25], v[160:163], v[208:211], v[22:25]
	v_mfma_f32_16x16x32_bf16 v[18:21], v[168:171], v[208:211], v[18:21]
	v_mfma_f32_16x16x32_bf16 v[6:9], v[160:163], v[216:219], v[6:9]
	v_mfma_f32_16x16x32_bf16 v[2:5], v[168:171], v[216:219], v[2:5]
	v_mfma_f32_16x16x32_bf16 v[54:57], v[164:167], v[180:183], v[54:57]
	v_mfma_f32_16x16x32_bf16 v[50:53], v[172:175], v[180:183], v[50:53]
	v_mfma_f32_16x16x32_bf16 v[38:41], v[164:167], v[204:207], v[38:41]
	v_mfma_f32_16x16x32_bf16 v[34:37], v[172:175], v[204:207], v[34:37]
	v_mfma_f32_16x16x32_bf16 v[22:25], v[164:167], v[212:215], v[22:25]
	v_mfma_f32_16x16x32_bf16 v[18:21], v[172:175], v[212:215], v[18:21]
	v_mfma_f32_16x16x32_bf16 v[6:9], v[164:167], v[232:235], v[6:9]
	v_mfma_f32_16x16x32_bf16 v[2:5], v[172:175], v[232:235], v[2:5]
	s_barrier
	s_add_i32 s57, s57, 2
	s_add_u32 s43, s43, 0x100
	s_addc_u32 s56, s56, 0
	s_add_u32 s50, s50, 0x100
	s_addc_u32 s51, s51, 0
	s_cmp_gt_u32 s57, 29
	s_cbranch_scc0 .LBB0_118
	s_setprio 0
	s_and_b64 vcc, exec, s[16:17]
	s_cbranch_vccz .LBB0_121
	s_barrier

; template <int PASS>
; __device__ __forceinline__ void lru_tile(const Ctx& C, int l, int ct, int hd, const LruHead& HD) {
;     ...
;                     if (k == 3 && lastchunk && t >= 125) {
;                         float* o = C.out + O_CONVP + ((size_t)(l * 2 + T.sidx) * 3 + (t - 125)) * GW + chg;
;                         *(f32x4*)o = (f32x4){xv[0], xv[1], xv[2], xv[3]}; *(f32x4*)(o + 4) = (f32x4){xv[4], xv[5], xv[6], xv[7]}; } }
.LBB0_1243:
	s_or_b64 exec, exec, s[24:25]
	s_and_b64 s[2:3], s[62:63], s[60:61]
	s_and_saveexec_b64 s[24:25], s[2:3]
	s_cbranch_execz .LBB0_910
	s_add_u32 s2, s7, s22
	s_addc_u32 s3, s92, s23
	global_store_dwordx4 v58, v[6:9], s[2:3]
	global_store_dwordx4 v58, v[2:5], s[2:3] offset:16
	s_branch .LBB0_910
	s_nop 0
	s_nop 0
	s_nop 0
	s_nop 0
	s_nop 0
	s_nop 0
	s_nop 0
	s_nop 0
	s_nop 0
	s_nop 0
	s_nop 0
	s_nop 0
	s_nop 0
	s_nop 0
	s_nop 0
	s_nop 0

; #define PG8_STAGE(bufoff, gbase, voff) do { _Pragma("unroll") for (int _i = 0; _i < 2; ++_i) \
;         __builtin_amdgcn_global_load_lds((const unsigned*)((const char*)(gbase) + (voff)[_i]), (PG8_LAS unsigned*)(lds + (bufoff) + ldsw + _i * 8192), 16, 0, 0); } while (0)
; #define PG8_LDA(dst, b, h) do { _Pragma("unroll") for (int m = 0; m < 4; ++m) _Pragma("unroll") for (int k = 0; k < 2; ++k) dst[m][k] = *(const PG8_LAS bf16x8*)(lds + PG8_SA(b, h) + aoff + m * 2048 + k * 1024); } while (0)
; #define PG8_LDB(dst, b, h) do { _Pragma("unroll") for (int n = 0; n < 2; ++n) _Pragma("unroll") for (int k = 0; k < 2; ++k) dst[n][k] = *(const PG8_LAS bf16x8*)(lds + PG8_SB(b, h) + boff + n * 2048 + k * 1024); } while (0)
; #define PG8_MMA(ai, bj, At, Bt) do { __builtin_amdgcn_s_setprio(1); _Pragma("unroll") for (int m = 0; m < 4; ++m) _Pragma("unroll") for (int n = 0; n < 2; ++n) _Pragma("unroll") for (int k = 0; k < 2; ++k) \
;         acc[ai][bj][m][n] = __builtin_amdgcn_mfma_f32_16x16x32_bf16(Bt[n][k], At[m][k], acc[ai][bj][m][n], 0, 0, 0); __builtin_amdgcn_s_setprio(0); } while (0)
; #define PG8_WAIT_V(n) asm volatile("s_waitcnt vmcnt(" #n ")" ::: "memory")
; #define PG8_WAIT_L(n) asm volatile("s_waitcnt lgkmcnt(" #n ")" ::: "memory")
; #define PG8_BAR __builtin_amdgcn_s_barrier()
; #define PG8_SCHED __builtin_amdgcn_sched_barrier(0)
; template <class Epi, class Sched, bool ALIGN_EPI = false, bool SP2 = false>
; __device__ __forceinline__ void gemm_phase(PG8_LAS unsigned char* lds, const Gemm g, const Sched& S, const Epi& E) {
;     ...
;             const char* a2 = last ? nA : cA + (size_t)(t + 2) * kstep; const char* b2 = last ? nB : cB + (size_t)(t + 2) * kstep;
;             const char* a3 = a2 + kstep; const char* b3 = b2 + kstep;
;             if (last && has_next) S.a_ready(nxt);
;             if constexpr (SP2) {
;             PG8_LDB(B0, 0, 0); PG8_LDB(B1, 0, 1); PG8_SCHED; PG8_LDA(At, 0, 0); PG8_STAGE(PG8_SA(1, 1), a1 + hstep, voffA);
;             PG8_WAIT_V(8); PG8_WAIT_L(0); PG8_BAR; PG8_MMA(0, 0, At, B0); PG8_MMA(0, 1, At, B1); PG8_BAR; PG8_SCHED;
;             PG8_LDA(At, 0, 1); PG8_STAGE(PG8_SB(0, 0), b2, voffB); PG8_STAGE(PG8_SB(0, 1), b2 + hstep, voffB); PG8_STAGE(PG8_SA(0, 0), a2, voffA);
.Lmy_p5_prio_done:
.LBB0_1334:
	s_add_i32 s63, s46, 2
	s_add_u32 s47, s22, 0xfff80080
	s_addc_u32 s65, s23, -1
	s_add_i32 s77, 0, 0x10000
	s_cmp_eq_u32 s2, s46
	s_cselect_b32 s83, s79, s65
	s_cselect_b32 s82, s78, s47
	v_add_u32_e32 v0, s77, v232
	s_cselect_b32 s47, s81, s45
	s_cselect_b32 s46, s80, s3
	s_add_i32 s65, 0, 0x14000
	s_waitcnt lgkmcnt(0)
	ds_read_b128 v[132:135], v0
	ds_read_b128 v[136:139], v0 offset:1024
	ds_read_b128 v[140:143], v0 offset:2048
	ds_read_b128 v[144:147], v0 offset:3072
	v_add_u32_e32 v0, s65, v232
	ds_read_b128 v[148:151], v0
	ds_read_b128 v[152:155], v0 offset:1024
	ds_read_b128 v[156:159], v0 offset:2048
	ds_read_b128 v[160:163], v0 offset:3072
	v_lshl_add_u64 v[2:3], s[22:23], 0, v[208:209]
	s_add_i32 m0, s35, 0xc000
	ds_read_b128 v[164:167], v234
	ds_read_b128 v[168:171], v234 offset:1024
	ds_read_b128 v[172:175], v234 offset:2048
	ds_read_b128 v[176:179], v234 offset:3072
	ds_read_b128 v[180:183], v234 offset:4096
	ds_read_b128 v[210:213], v234 offset:5120
	ds_read_b128 v[214:217], v234 offset:6144
	ds_read_b128 v[236:239], v234 offset:7168
	global_load_lds_dwordx4 v[2:3], off
	v_lshl_add_u64 v[2:3], s[22:23], 0, v[206:207]
	s_add_i32 m0, s35, 0xe000
	s_nop 0
	global_load_lds_dwordx4 v[2:3], off
	s_waitcnt vmcnt(8)
	s_waitcnt lgkmcnt(0)
	s_barrier
	v_mfma_f32_16x16x32_bf16 v[128:131], v[132:135], v[164:167], v[128:131]
	v_mfma_f32_16x16x32_bf16 v[124:127], v[140:143], v[164:167], v[124:127]
	v_mfma_f32_16x16x32_bf16 v[120:123], v[132:135], v[172:175], v[120:123]
	v_mfma_f32_16x16x32_bf16 v[116:119], v[140:143], v[172:175], v[116:119]
	v_mfma_f32_16x16x32_bf16 v[112:115], v[132:135], v[180:183], v[112:115]
	v_mfma_f32_16x16x32_bf16 v[108:111], v[140:143], v[180:183], v[108:111]
	v_mfma_f32_16x16x32_bf16 v[104:107], v[132:135], v[214:217], v[104:107]
	v_mfma_f32_16x16x32_bf16 v[100:103], v[140:143], v[214:217], v[100:103]
	v_mfma_f32_16x16x32_bf16 v[128:131], v[136:139], v[168:171], v[128:131]
	v_mfma_f32_16x16x32_bf16 v[124:127], v[144:147], v[168:171], v[124:127]
	v_mfma_f32_16x16x32_bf16 v[120:123], v[136:139], v[176:179], v[120:123]
	v_mfma_f32_16x16x32_bf16 v[116:119], v[144:147], v[176:179], v[116:119]
	v_mfma_f32_16x16x32_bf16 v[112:115], v[136:139], v[210:213], v[112:115]
	v_mfma_f32_16x16x32_bf16 v[108:111], v[144:147], v[210:213], v[108:111]
	v_mfma_f32_16x16x32_bf16 v[104:107], v[136:139], v[236:239], v[104:107]
	v_mfma_f32_16x16x32_bf16 v[100:103], v[144:147], v[236:239], v[100:103]
	v_mfma_f32_16x16x32_bf16 v[96:99], v[148:151], v[164:167], v[96:99]
	v_mfma_f32_16x16x32_bf16 v[92:95], v[156:159], v[164:167], v[92:95]
	v_mfma_f32_16x16x32_bf16 v[88:91], v[148:151], v[172:175], v[88:91]
	v_mfma_f32_16x16x32_bf16 v[84:87], v[156:159], v[172:175], v[84:87]
	v_mfma_f32_16x16x32_bf16 v[80:83], v[148:151], v[180:183], v[80:83]
	v_mfma_f32_16x16x32_bf16 v[76:79], v[156:159], v[180:183], v[76:79]
	v_mfma_f32_16x16x32_bf16 v[72:75], v[148:151], v[214:217], v[72:75]
	v_mfma_f32_16x16x32_bf16 v[68:71], v[156:159], v[214:217], v[68:71]
	v_mfma_f32_16x16x32_bf16 v[96:99], v[152:155], v[168:171], v[96:99]
	v_mfma_f32_16x16x32_bf16 v[92:95], v[160:163], v[168:171], v[92:95]
	v_mfma_f32_16x16x32_bf16 v[88:91], v[152:155], v[176:179], v[88:91]
	v_mfma_f32_16x16x32_bf16 v[84:87], v[160:163], v[176:179], v[84:87]
	v_mfma_f32_16x16x32_bf16 v[80:83], v[152:155], v[210:213], v[80:83]
	v_mfma_f32_16x16x32_bf16 v[76:79], v[160:163], v[210:213], v[76:79]
	v_mfma_f32_16x16x32_bf16 v[72:75], v[152:155], v[236:239], v[72:75]
	v_mfma_f32_16x16x32_bf16 v[68:71], v[160:163], v[236:239], v[68:71]
	s_barrier
	s_add_i32 s77, s77, s33
	v_lshl_add_u64 v[218:219], s[46:47], 0, v[200:201]
	s_mov_b32 m0, s77
	ds_read_b128 v[164:167], v234 offset:16384
	ds_read_b128 v[168:171], v234 offset:17408
	ds_read_b128 v[172:175], v234 offset:18432
	ds_read_b128 v[176:179], v234 offset:19456
	ds_read_b128 v[180:183], v234 offset:20480
	ds_read_b128 v[210:213], v234 offset:21504
	ds_read_b128 v[214:217], v234 offset:22528
	ds_read_b128 v[236:239], v234 offset:23552
	global_load_lds_dwordx4 v[218:219], off
	s_add_i32 m0, s77, 0x2000
	s_add_u32 s92, s46, 0x80000
	v_lshl_add_u64 v[240:241], s[46:47], 0, v[204:205]
	s_addc_u32 s93, s47, 0
	s_add_i32 s65, s65, s33
	global_load_lds_dwordx4 v[240:241], off
	v_lshl_add_u64 v[2:3], s[92:93], 0, v[200:201]
	s_mov_b32 m0, s65
	v_lshl_add_u64 v[242:243], s[82:83], 0, v[184:185]
	global_load_lds_dwordx4 v[2:3], off
	v_lshl_add_u64 v[2:3], s[92:93], 0, v[204:205]
	s_add_i32 m0, s65, 0x2000
	v_lshl_add_u64 v[244:245], s[82:83], 0, v[202:203]
	global_load_lds_dwordx4 v[2:3], off
	s_mov_b32 m0, s35
	s_nop 0
	global_load_lds_dwordx4 v[242:243], off
	s_mov_b32 m0, s36
	s_nop 0
	global_load_lds_dwordx4 v[244:245], off
	s_waitcnt vmcnt(8)
	s_waitcnt lgkmcnt(0)
	s_barrier
; #define PG8_STAGE(bufoff, gbase, voff) do { _Pragma("unroll") for (int _i = 0; _i < 2; ++_i) \
;         __builtin_amdgcn_global_load_lds((const unsigned*)((const char*)(gbase) + (voff)[_i]), (PG8_LAS unsigned*)(lds + (bufoff) + ldsw + _i * 8192), 16, 0, 0); } while (0)
; #define PG8_LDA(dst, b, h) do { _Pragma("unroll") for (int m = 0; m < 4; ++m) _Pragma("unroll") for (int k = 0; k < 2; ++k) dst[m][k] = *(const PG8_LAS bf16x8*)(lds + PG8_SA(b, h) + aoff + m * 2048 + k * 1024); } while (0)
; #define PG8_LDB(dst, b, h) do { _Pragma("unroll") for (int n = 0; n < 2; ++n) _Pragma("unroll") for (int k = 0; k < 2; ++k) dst[n][k] = *(const PG8_LAS bf16x8*)(lds + PG8_SB(b, h) + boff + n * 2048 + k * 1024); } while (0)
; #define PG8_MMA(ai, bj, At, Bt) do { __builtin_amdgcn_s_setprio(1); _Pragma("unroll") for (int m = 0; m < 4; ++m) _Pragma("unroll") for (int n = 0; n < 2; ++n) _Pragma("unroll") for (int k = 0; k < 2; ++k) \
;         acc[ai][bj][m][n] = __builtin_amdgcn_mfma_f32_16x16x32_bf16(Bt[n][k], At[m][k], acc[ai][bj][m][n], 0, 0, 0); __builtin_amdgcn_s_setprio(0); } while (0)
; #define PG8_WAIT_V(n) asm volatile("s_waitcnt vmcnt(" #n ")" ::: "memory")
; #define PG8_WAIT_L(n) asm volatile("s_waitcnt lgkmcnt(" #n ")" ::: "memory")
; #define PG8_BAR __builtin_amdgcn_s_barrier()
; #define PG8_SCHED __builtin_amdgcn_sched_barrier(0)
; template <class Epi, class Sched, bool ALIGN_EPI = false, bool SP2 = false>
; __device__ __forceinline__ void gemm_phase(PG8_LAS unsigned char* lds, const Gemm g, const Sched& S, const Epi& E) {
;     ...
;             PG8_WAIT_V(8); PG8_WAIT_L(0); PG8_BAR; PG8_MMA(1, 0, At, B0); PG8_MMA(1, 1, At, B1); PG8_BAR; PG8_SCHED;
;             PG8_LDB(B0, 1, 0); PG8_LDB(B1, 1, 1); PG8_SCHED; PG8_LDA(At, 1, 0); PG8_STAGE(PG8_SA(0, 1), a2 + hstep, voffA);
;             PG8_WAIT_V(8); PG8_WAIT_L(0); PG8_BAR; PG8_MMA(0, 0, At, B0); PG8_MMA(0, 1, At, B1); PG8_BAR; PG8_SCHED;
	v_mfma_f32_16x16x32_bf16 v[64:67], v[132:135], v[164:167], v[64:67]
	v_mfma_f32_16x16x32_bf16 v[60:63], v[140:143], v[164:167], v[60:63]
	v_mfma_f32_16x16x32_bf16 v[56:59], v[132:135], v[172:175], v[56:59]
	v_mfma_f32_16x16x32_bf16 v[52:55], v[140:143], v[172:175], v[52:55]
	v_mfma_f32_16x16x32_bf16 v[48:51], v[132:135], v[180:183], v[48:51]
	v_mfma_f32_16x16x32_bf16 v[44:47], v[140:143], v[180:183], v[44:47]
	v_mfma_f32_16x16x32_bf16 v[40:43], v[132:135], v[214:217], v[40:43]
	v_mfma_f32_16x16x32_bf16 v[36:39], v[140:143], v[214:217], v[36:39]
	v_mfma_f32_16x16x32_bf16 v[64:67], v[136:139], v[168:171], v[64:67]
	v_mfma_f32_16x16x32_bf16 v[60:63], v[144:147], v[168:171], v[60:63]
	v_mfma_f32_16x16x32_bf16 v[56:59], v[136:139], v[176:179], v[56:59]
	v_mfma_f32_16x16x32_bf16 v[52:55], v[144:147], v[176:179], v[52:55]
	v_mfma_f32_16x16x32_bf16 v[48:51], v[136:139], v[210:213], v[48:51]
	v_mfma_f32_16x16x32_bf16 v[44:47], v[144:147], v[210:213], v[44:47]
	v_mfma_f32_16x16x32_bf16 v[40:43], v[136:139], v[236:239], v[40:43]
	v_mfma_f32_16x16x32_bf16 v[36:39], v[144:147], v[236:239], v[36:39]
	v_mfma_f32_16x16x32_bf16 v[32:35], v[148:151], v[164:167], v[32:35]
	v_mfma_f32_16x16x32_bf16 v[28:31], v[156:159], v[164:167], v[28:31]
	v_mfma_f32_16x16x32_bf16 v[24:27], v[148:151], v[172:175], v[24:27]
	v_mfma_f32_16x16x32_bf16 v[20:23], v[156:159], v[172:175], v[20:23]
	v_mfma_f32_16x16x32_bf16 v[16:19], v[148:151], v[180:183], v[16:19]
	v_mfma_f32_16x16x32_bf16 v[12:15], v[156:159], v[180:183], v[12:15]
	v_mfma_f32_16x16x32_bf16 v[8:11], v[148:151], v[214:217], v[8:11]
	v_mfma_f32_16x16x32_bf16 v[2:5], v[156:159], v[214:217], v[4:7]
	v_mfma_f32_16x16x32_bf16 v[32:35], v[152:155], v[168:171], v[32:35]
	v_mfma_f32_16x16x32_bf16 v[28:31], v[160:163], v[168:171], v[28:31]
	v_mfma_f32_16x16x32_bf16 v[24:27], v[152:155], v[176:179], v[24:27]
	v_mfma_f32_16x16x32_bf16 v[20:23], v[160:163], v[176:179], v[20:23]
	v_mfma_f32_16x16x32_bf16 v[16:19], v[152:155], v[210:213], v[16:19]
	v_mfma_f32_16x16x32_bf16 v[12:15], v[160:163], v[210:213], v[12:15]
	v_mfma_f32_16x16x32_bf16 v[8:11], v[152:155], v[236:239], v[8:11]
	v_mfma_f32_16x16x32_bf16 v[2:5], v[160:163], v[236:239], v[2:5]
	s_barrier
	s_add_i32 s65, 0, 0x18000
	v_add_u32_e32 v0, s65, v232
	s_add_i32 s77, 0, 0x1c000
	ds_read_b128 v[132:135], v0
	ds_read_b128 v[136:139], v0 offset:1024
	ds_read_b128 v[140:143], v0 offset:2048
	ds_read_b128 v[144:147], v0 offset:3072
	v_add_u32_e32 v0, s77, v232
	ds_read_b128 v[148:151], v0
	ds_read_b128 v[152:155], v0 offset:1024
	ds_read_b128 v[156:159], v0 offset:2048
	ds_read_b128 v[160:163], v0 offset:3072
	s_add_u32 s82, s82, 0x80000
	s_addc_u32 s83, s83, 0
	s_mov_b32 m0, s37
	v_lshl_add_u64 v[6:7], s[82:83], 0, v[184:185]
	ds_read_b128 v[164:167], v234 offset:32768
	ds_read_b128 v[168:171], v234 offset:33792
	ds_read_b128 v[172:175], v234 offset:34816
	ds_read_b128 v[176:179], v234 offset:35840
	ds_read_b128 v[180:183], v234 offset:36864
	ds_read_b128 v[210:213], v234 offset:37888
	ds_read_b128 v[214:217], v234 offset:38912
	ds_read_b128 v[236:239], v234 offset:39936
	global_load_lds_dwordx4 v[6:7], off
	v_lshl_add_u64 v[6:7], s[82:83], 0, v[202:203]
	s_mov_b32 m0, s67
	s_nop 0
	global_load_lds_dwordx4 v[6:7], off
	s_waitcnt vmcnt(8)
	s_waitcnt lgkmcnt(0)
	s_barrier
	v_mfma_f32_16x16x32_bf16 v[128:131], v[132:135], v[164:167], v[128:131]
	v_mfma_f32_16x16x32_bf16 v[124:127], v[140:143], v[164:167], v[124:127]
	v_mfma_f32_16x16x32_bf16 v[120:123], v[132:135], v[172:175], v[120:123]
	v_mfma_f32_16x16x32_bf16 v[116:119], v[140:143], v[172:175], v[116:119]
	v_mfma_f32_16x16x32_bf16 v[112:115], v[132:135], v[180:183], v[112:115]
	v_mfma_f32_16x16x32_bf16 v[108:111], v[140:143], v[180:183], v[108:111]
	v_mfma_f32_16x16x32_bf16 v[104:107], v[132:135], v[214:217], v[104:107]
	v_mfma_f32_16x16x32_bf16 v[100:103], v[140:143], v[214:217], v[100:103]
	v_mfma_f32_16x16x32_bf16 v[128:131], v[136:139], v[168:171], v[128:131]
	v_mfma_f32_16x16x32_bf16 v[124:127], v[144:147], v[168:171], v[124:127]
	v_mfma_f32_16x16x32_bf16 v[120:123], v[136:139], v[176:179], v[120:123]
	v_mfma_f32_16x16x32_bf16 v[116:119], v[144:147], v[176:179], v[116:119]
	v_mfma_f32_16x16x32_bf16 v[112:115], v[136:139], v[210:213], v[112:115]
	v_mfma_f32_16x16x32_bf16 v[108:111], v[144:147], v[210:213], v[108:111]
	v_mfma_f32_16x16x32_bf16 v[104:107], v[136:139], v[236:239], v[104:107]
	v_mfma_f32_16x16x32_bf16 v[100:103], v[144:147], v[236:239], v[100:103]
	v_mfma_f32_16x16x32_bf16 v[96:99], v[148:151], v[164:167], v[96:99]
	v_mfma_f32_16x16x32_bf16 v[92:95], v[156:159], v[164:167], v[92:95]
	v_mfma_f32_16x16x32_bf16 v[88:91], v[148:151], v[172:175], v[88:91]
	v_mfma_f32_16x16x32_bf16 v[84:87], v[156:159], v[172:175], v[84:87]
	v_mfma_f32_16x16x32_bf16 v[80:83], v[148:151], v[180:183], v[80:83]
	v_mfma_f32_16x16x32_bf16 v[76:79], v[156:159], v[180:183], v[76:79]
	v_mfma_f32_16x16x32_bf16 v[72:75], v[148:151], v[214:217], v[72:75]
	v_mfma_f32_16x16x32_bf16 v[68:71], v[156:159], v[214:217], v[68:71]
	v_mfma_f32_16x16x32_bf16 v[96:99], v[152:155], v[168:171], v[96:99]
	v_mfma_f32_16x16x32_bf16 v[92:95], v[160:163], v[168:171], v[92:95]
	v_mfma_f32_16x16x32_bf16 v[88:91], v[152:155], v[176:179], v[88:91]
	v_mfma_f32_16x16x32_bf16 v[84:87], v[160:163], v[176:179], v[84:87]
	v_mfma_f32_16x16x32_bf16 v[80:83], v[152:155], v[210:213], v[80:83]
	v_mfma_f32_16x16x32_bf16 v[76:79], v[160:163], v[210:213], v[76:79]
	v_mfma_f32_16x16x32_bf16 v[72:75], v[152:155], v[236:239], v[72:75]
	v_mfma_f32_16x16x32_bf16 v[68:71], v[160:163], v[236:239], v[68:71]
	s_barrier
; #define PG8_STAGE(bufoff, gbase, voff) do { _Pragma("unroll") for (int _i = 0; _i < 2; ++_i) \
;         __builtin_amdgcn_global_load_lds((const unsigned*)((const char*)(gbase) + (voff)[_i]), (PG8_LAS unsigned*)(lds + (bufoff) + ldsw + _i * 8192), 16, 0, 0); } while (0)
; #define PG8_LDA(dst, b, h) do { _Pragma("unroll") for (int m = 0; m < 4; ++m) _Pragma("unroll") for (int k = 0; k < 2; ++k) dst[m][k] = *(const PG8_LAS bf16x8*)(lds + PG8_SA(b, h) + aoff + m * 2048 + k * 1024); } while (0)
; #define PG8_MMA(ai, bj, At, Bt) do { __builtin_amdgcn_s_setprio(1); _Pragma("unroll") for (int m = 0; m < 4; ++m) _Pragma("unroll") for (int n = 0; n < 2; ++n) _Pragma("unroll") for (int k = 0; k < 2; ++k) \
;         acc[ai][bj][m][n] = __builtin_amdgcn_mfma_f32_16x16x32_bf16(Bt[n][k], At[m][k], acc[ai][bj][m][n], 0, 0, 0); __builtin_amdgcn_s_setprio(0); } while (0)
; #define PG8_WAIT_V(n) asm volatile("s_waitcnt vmcnt(" #n ")" ::: "memory")
; #define PG8_WAIT_L(n) asm volatile("s_waitcnt lgkmcnt(" #n ")" ::: "memory")
; #define PG8_BAR __builtin_amdgcn_s_barrier()
; #define PG8_SCHED __builtin_amdgcn_sched_barrier(0)
; template <class Epi, class Sched, bool ALIGN_EPI = false, bool SP2 = false>
; __device__ __forceinline__ void gemm_phase(PG8_LAS unsigned char* lds, const Gemm g, const Sched& S, const Epi& E) {
;     ...
;             PG8_LDA(At, 1, 1); PG8_STAGE(PG8_SB(1, 0), b3, voffB); PG8_STAGE(PG8_SB(1, 1), b3 + hstep, voffB); PG8_STAGE(PG8_SA(1, 0), a3, voffA);
;             PG8_WAIT_V(8); PG8_WAIT_L(0); PG8_BAR; PG8_MMA(1, 0, At, B0); PG8_MMA(1, 1, At, B1); PG8_BAR; PG8_SCHED;
;     ...
;         }
;         if constexpr (ALIGN_EPI) { if (wr == 0) PG8_BAR; }
	s_add_i32 s65, s65, s33
	v_lshl_add_u64 v[6:7], v[218:219], 0, s[0:1]
	s_mov_b32 m0, s65
	ds_read_b128 v[164:167], v234 offset:49152
	ds_read_b128 v[168:171], v234 offset:50176
	ds_read_b128 v[172:175], v234 offset:51200
	ds_read_b128 v[176:179], v234 offset:52224
	ds_read_b128 v[180:183], v234 offset:53248
	ds_read_b128 v[210:213], v234 offset:54272
	ds_read_b128 v[214:217], v234 offset:55296
	ds_read_b128 v[236:239], v234 offset:56320
	global_load_lds_dwordx4 v[6:7], off
	s_add_i32 m0, s65, 0x2000
	s_add_u32 s46, s46, 0x80080
	v_lshl_add_u64 v[6:7], v[240:241], 0, s[0:1]
	s_addc_u32 s47, s47, 0
	s_add_i32 s65, s77, s33
	global_load_lds_dwordx4 v[6:7], off
	v_lshl_add_u64 v[6:7], s[46:47], 0, v[200:201]
	s_mov_b32 m0, s65
	s_nop 0
	global_load_lds_dwordx4 v[6:7], off
	v_lshl_add_u64 v[6:7], s[46:47], 0, v[204:205]
	s_add_i32 m0, s65, 0x2000
	s_nop 0
	global_load_lds_dwordx4 v[6:7], off
	v_lshl_add_u64 v[6:7], v[242:243], 0, s[0:1]
	s_mov_b32 m0, s71
	s_nop 0
	global_load_lds_dwordx4 v[6:7], off
	v_lshl_add_u64 v[6:7], v[244:245], 0, s[0:1]
	s_mov_b32 m0, s89
	s_nop 0
	global_load_lds_dwordx4 v[6:7], off
	s_waitcnt vmcnt(8)
	s_waitcnt lgkmcnt(0)
	s_barrier
	v_mfma_f32_16x16x32_bf16 v[64:67], v[132:135], v[164:167], v[64:67]
	v_mfma_f32_16x16x32_bf16 v[60:63], v[140:143], v[164:167], v[60:63]
	v_mfma_f32_16x16x32_bf16 v[56:59], v[132:135], v[172:175], v[56:59]
	v_mfma_f32_16x16x32_bf16 v[52:55], v[140:143], v[172:175], v[52:55]
	v_mfma_f32_16x16x32_bf16 v[48:51], v[132:135], v[180:183], v[48:51]
	v_mfma_f32_16x16x32_bf16 v[44:47], v[140:143], v[180:183], v[44:47]
	v_mfma_f32_16x16x32_bf16 v[40:43], v[132:135], v[214:217], v[40:43]
	v_mfma_f32_16x16x32_bf16 v[36:39], v[140:143], v[214:217], v[36:39]
	v_mfma_f32_16x16x32_bf16 v[64:67], v[136:139], v[168:171], v[64:67]
	v_mfma_f32_16x16x32_bf16 v[60:63], v[144:147], v[168:171], v[60:63]
	v_mfma_f32_16x16x32_bf16 v[56:59], v[136:139], v[176:179], v[56:59]
	v_mfma_f32_16x16x32_bf16 v[52:55], v[144:147], v[176:179], v[52:55]
	v_mfma_f32_16x16x32_bf16 v[48:51], v[136:139], v[210:213], v[48:51]
	v_mfma_f32_16x16x32_bf16 v[44:47], v[144:147], v[210:213], v[44:47]
	v_mfma_f32_16x16x32_bf16 v[40:43], v[136:139], v[236:239], v[40:43]
	v_mfma_f32_16x16x32_bf16 v[36:39], v[144:147], v[236:239], v[36:39]
	v_mfma_f32_16x16x32_bf16 v[32:35], v[148:151], v[164:167], v[32:35]
	v_mfma_f32_16x16x32_bf16 v[28:31], v[156:159], v[164:167], v[28:31]
	v_mfma_f32_16x16x32_bf16 v[24:27], v[148:151], v[172:175], v[24:27]
	v_mfma_f32_16x16x32_bf16 v[20:23], v[156:159], v[172:175], v[20:23]
	v_mfma_f32_16x16x32_bf16 v[16:19], v[148:151], v[180:183], v[16:19]
	v_mfma_f32_16x16x32_bf16 v[12:15], v[156:159], v[180:183], v[12:15]
	v_mfma_f32_16x16x32_bf16 v[6:9], v[148:151], v[214:217], v[8:11]
	v_mfma_f32_16x16x32_bf16 v[2:5], v[156:159], v[214:217], v[2:5]
	v_mfma_f32_16x16x32_bf16 v[32:35], v[152:155], v[168:171], v[32:35]
	v_mfma_f32_16x16x32_bf16 v[28:31], v[160:163], v[168:171], v[28:31]
	v_mfma_f32_16x16x32_bf16 v[24:27], v[152:155], v[176:179], v[24:27]
	v_mfma_f32_16x16x32_bf16 v[20:23], v[160:163], v[176:179], v[20:23]
	v_mfma_f32_16x16x32_bf16 v[16:19], v[152:155], v[210:213], v[16:19]
	v_mfma_f32_16x16x32_bf16 v[12:15], v[160:163], v[210:213], v[12:15]
	v_mfma_f32_16x16x32_bf16 v[8:11], v[152:155], v[236:239], v[6:9]
	v_mfma_f32_16x16x32_bf16 v[4:7], v[160:163], v[236:239], v[2:5]
	s_barrier
	s_add_u32 s3, s3, 0x100
	s_addc_u32 s45, s45, 0
	s_add_u32 s22, s22, 0x100
	s_addc_u32 s23, s23, 0
	s_cmp_ge_i32 s63, s86
	s_mov_b32 s46, s63
	s_cbranch_scc0 .LBB0_1334
	s_setprio 0
	s_and_b64 vcc, exec, s[60:61]
	s_cbranch_vccz .LBB0_1337
	s_barrier

; template <class Epi, class Sched, bool ALIGN_EPI = false, bool SP2 = false>
; __device__ __forceinline__ void gemm_phase(PG8_LAS unsigned char* lds, const Gemm g, const Sched& S, const Epi& E) {
;     ...
;         const bool has_next = S.next(ui + 1, nxt);
;         const char* nA = has_next ? (const char*)g.A + (size_t)nxt.pm * tstep + (size_t)nxt.kt0 * kstep : cA; const char* nB = has_next ? (const char*)g.Bt + (size_t)nxt.pn * tstep + (size_t)nxt.kt0 * kstep : cB;
.LBB0_1400:
	s_ashr_i32 s63, s62, 31
	s_lshl_b64 s[2:3], s[62:63], 20
	s_add_u32 s45, s12, s2
	s_addc_u32 s63, s13, s3
	s_ashr_i32 s77, s76, 31
	s_lshl_b64 s[2:3], s[76:77], 7
	s_add_u32 s78, s45, s2
	s_addc_u32 s79, s63, s3
	s_and_b64 vcc, exec, s[42:43]
	s_mov_b64 s[80:81], s[22:23]
	s_cbranch_vccz .LBB0_1332
	s_branch .LBB0_1333
	s_nop 0
	s_nop 0
	s_nop 0
	s_nop 0
	s_nop 0
	s_nop 0
	s_nop 0
	s_nop 0
	s_nop 0
	s_nop 0
	s_nop 0
	s_nop 0
	s_nop 0
	s_nop 0
	s_nop 0
	s_nop 0
	s_nop 0
	s_nop 0
	s_nop 0
	s_nop 0
	s_nop 0
	s_nop 0
	s_nop 0
	s_nop 0
	s_nop 0
	s_nop 0
	s_nop 0
	s_nop 0
	s_nop 0
	s_nop 0
	s_nop 0
	s_nop 0
	s_nop 0
	s_nop 0
	s_nop 0
	s_nop 0
	s_nop 0
	s_nop 0
	s_nop 0
	s_nop 0
	s_nop 0
	s_nop 0
	s_nop 0
	s_nop 0
	s_nop 0
	s_nop 0
	s_nop 0
	s_nop 0
	s_nop 0
	s_nop 0
	s_nop 0
	s_nop 0
	s_nop 0
	s_nop 0
	s_nop 0
	s_nop 0
	s_nop 0
	s_nop 0
	s_nop 0
	s_nop 0
	s_nop 0
	s_nop 0
	s_nop 0
	s_nop 0
	s_nop 0
	s_nop 0
	s_nop 0
	s_nop 0
	s_nop 0
	s_nop 0
	s_nop 0
	s_nop 0
	s_nop 0
	s_nop 0
	s_nop 0
	s_nop 0
	s_nop 0
	s_nop 0
	s_nop 0
	s_nop 0
	s_nop 0
	s_nop 0
	s_nop 0
	s_nop 0
	s_nop 0
	s_nop 0
	s_nop 0
	s_nop 0
	s_nop 0
	s_nop 0
	s_nop 0
	s_nop 0
	s_nop 0
	s_nop 0
	s_nop 0
	s_nop 0
	s_nop 0
	s_nop 0
	s_nop 0
	s_nop 0
	s_nop 0
	s_nop 0
	s_nop 0
	s_nop 0
	s_nop 0
	s_nop 0
	s_nop 0

; __device__ __forceinline__ unsigned pk2(float lo, float hi) { unsigned r; asm volatile("v_cvt_pk_bf16_f32 %0, %1, %2" : "=v"(r) : "v"(lo), "v"(hi)); return r; }
;     __device__ __forceinline__ void operator()(const f32x4 (&acc)[2][2][4][2], const Unit& u, int wr, int wc, int fr, int fq) const {
;         const int row0 = u.pm * BM + wr * 64 + fr, col0 = u.pn * HALF + wc * 32 + 8 * fq;
;         float rs[2][4];
; #pragma unroll
;         for (int ai = 0; ai < 2; ++ai)
; #pragma unroll
;             for (int m = 0; m < 4; ++m) rs[ai][m] = ssq[row0 + ai * HALF + m * 16];
; #pragma unroll
;         for (int ai = 0; ai < 2; ++ai)
; #pragma unroll
;             for (int m = 0; m < 4; ++m) { bf16_t* rowp = O + (size_t)(row0 + ai * HALF + m * 16) * DFF + col0; const float rsv = rsqrtf(rs[ai][m] * (1.f / D) + EPS);
;                 const float rs2 = rsv * rsv, nrs = -1.4426950409f * rsv;
;                 float v[8];
; #pragma unroll
;                 for (int n = 0; n < 2; ++n)
; #pragma unroll
;                     for (int j = 0; j < 4; ++j) {
;                         const float g0 = acc[ai][0][m][n][j], u0 = acc[ai][1][m][n][j];
;                         v[n * 4 + j] = (g0 * u0) * (rs2 * __builtin_amdgcn_rcpf(1.0f + __builtin_amdgcn_exp2f(g0 * nrs))); }
;                 u32x4 w; w.x = pk2(v[0], v[1]); w.y = pk2(v[2], v[3]); w.z = pk2(v[4], v[5]); w.w = pk2(v[6], v[7]);
;                 *(u32x4*)rowp = w; }
.LBB0_1490:
	v_lshl_add_u32 v144, s46, 8, v148
	v_ashrrev_i32_e32 v145, 31, v144
	v_lshl_add_u64 v[140:141], v[144:145], 2, s[12:13]
	flat_load_dword v146, v[140:141]
	flat_load_dword v164, v[140:141] offset:64
	flat_load_dword v162, v[140:141] offset:128
	flat_load_dword v160, v[140:141] offset:192
	flat_load_dword v158, v[140:141] offset:512
	flat_load_dword v156, v[140:141] offset:576
	flat_load_dword v154, v[140:141] offset:640
	flat_load_dword v152, v[140:141] offset:704
	v_mov_b32_e32 v166, v126
	v_lshl_or_b32 v142, s54, 7, v150
	v_ashrrev_i32_e32 v143, 31, v142
	v_mov_b64_e32 v[140:141], s[8:9]
	v_or_b32_e32 v165, 16, v144
	v_or_b32_e32 v163, 32, v144
	v_or_b32_e32 v161, 48, v144
	v_add_u32_e32 v159, 0x80, v144
	v_add_u32_e32 v157, 0x90, v144
	v_add_u32_e32 v155, 0xa0, v144
	v_add_u32_e32 v153, 0xb0, v144
	v_mad_i64_i32 v[144:145], s[2:3], v144, s34, v[140:141]
	s_mov_b64 s[22:23], -1
	s_mov_b64 s[56:57], s[94:95]
	s_waitcnt vmcnt(0) lgkmcnt(0)
	v_fmamk_f32 v146, v146, 0x3a000000, v223
	v_cmp_gt_f32_e32 vcc, s29, v146
	v_mul_f32_e32 v147, 0x4b800000, v146
	s_nop 0
	v_cndmask_b32_e32 v146, v146, v147, vcc
	v_rsq_f32_e32 v146, v146
	s_nop 0
	v_mul_f32_e32 v147, 0x45800000, v146
	v_cndmask_b32_e32 v146, v146, v147, vcc
	v_mul_f32_e32 v168, 0xbfb8aa3b, v146
	v_mul_f32_e32 v147, v146, v146
	v_mul_f32_e32 v146, v126, v168
	v_exp_f32_e32 v146, v146
	s_nop 0
	v_add_f32_e32 v146, 1.0, v146
	v_rcp_f32_e32 v167, v146
	v_mov_b32_e32 v146, v122
	v_mul_f32_e32 v122, v127, v168
	v_exp_f32_e32 v122, v122
	v_pk_mul_f32 v[166:167], v[146:147], v[166:167]
	v_mov_b32_e32 v146, v123
	v_mul_f32_e32 v126, v166, v167
	v_add_f32_e32 v122, 1.0, v122
	v_rcp_f32_e32 v167, v122
	v_mov_b32_e32 v166, v127
	v_pk_mul_f32 v[122:123], v[146:147], v[166:167]
	s_nop 0
	v_mul_f32_e32 v127, v122, v123
	v_mul_f32_e32 v122, v128, v168
	v_exp_f32_e32 v122, v122
	v_mov_b32_e32 v146, v124
	v_add_f32_e32 v122, 1.0, v122
	v_rcp_f32_e32 v123, v122
	v_mov_b32_e32 v122, v128
	v_pk_mul_f32 v[122:123], v[146:147], v[122:123]
	s_nop 0
	v_mul_f32_e32 v124, v122, v123
	v_mul_f32_e32 v122, v129, v168
	v_exp_f32_e32 v122, v122
	v_mov_b32_e32 v146, v125
	v_add_f32_e32 v122, 1.0, v122
	v_rcp_f32_e32 v123, v122
	v_mov_b32_e32 v122, v129
	v_pk_mul_f32 v[122:123], v[146:147], v[122:123]
	s_nop 0
	v_mul_f32_e32 v125, v122, v123
	v_mul_f32_e32 v122, v118, v168
	v_exp_f32_e32 v122, v122
	v_mov_b32_e32 v146, v114
	v_mul_f32_e32 v114, v119, v168
	v_exp_f32_e32 v114, v114
	v_add_f32_e32 v122, 1.0, v122
	v_rcp_f32_e32 v123, v122
	v_mov_b32_e32 v122, v118
	v_add_f32_e32 v114, 1.0, v114
	v_pk_mul_f32 v[122:123], v[146:147], v[122:123]
	s_nop 0
	v_mul_f32_e32 v118, v122, v123
	v_rcp_f32_e32 v123, v114
	v_mov_b32_e32 v146, v115
	v_mov_b32_e32 v122, v119
	v_pk_mul_f32 v[114:115], v[146:147], v[122:123]
	s_nop 0
	v_mul_f32_e32 v119, v114, v115
	v_mul_f32_e32 v114, v120, v168
	v_exp_f32_e32 v114, v114
	v_mov_b32_e32 v146, v116
	v_cvt_pk_bf16_f32 v116, v126, v127
	v_add_f32_e32 v114, 1.0, v114
	v_rcp_f32_e32 v115, v114
	v_mov_b32_e32 v114, v120
	v_pk_mul_f32 v[114:115], v[146:147], v[114:115]
	s_nop 0
	v_mul_f32_e32 v122, v114, v115
	v_mul_f32_e32 v114, v121, v168
	v_exp_f32_e32 v114, v114
	v_mov_b32_e32 v146, v117
	v_cvt_pk_bf16_f32 v117, v124, v125
	v_cvt_pk_bf16_f32 v118, v118, v119
	v_add_f32_e32 v114, 1.0, v114
	v_rcp_f32_e32 v115, v114
	v_mov_b32_e32 v114, v121
	v_pk_mul_f32 v[114:115], v[146:147], v[114:115]
	s_nop 0
	v_mul_f32_e32 v123, v114, v115
	v_lshlrev_b64 v[114:115], 1, v[142:143]
	v_lshl_add_u64 v[120:121], v[144:145], 0, v[114:115]
	v_cvt_pk_bf16_f32 v119, v122, v123
	flat_store_dwordx4 v[120:121], v[116:119]
	v_mov_b32_e32 v120, v110
	s_nop 0
	v_fmamk_f32 v118, v164, 0x3a000000, v223
	v_cmp_gt_f32_e32 vcc, s29, v118
	v_mul_f32_e32 v119, 0x4b800000, v118
	v_mad_i64_i32 v[116:117], s[2:3], v165, s34, v[140:141]
	v_cndmask_b32_e32 v118, v118, v119, vcc
	v_rsq_f32_e32 v118, v118
	s_nop 0
	v_mul_f32_e32 v119, 0x45800000, v118
	v_cndmask_b32_e32 v118, v118, v119, vcc
	v_mul_f32_e32 v122, 0xbfb8aa3b, v118
	v_mul_f32_e32 v119, v118, v118
	v_mul_f32_e32 v118, v110, v122
	v_exp_f32_e32 v118, v118
	s_nop 0
	v_add_f32_e32 v118, 1.0, v118
	v_rcp_f32_e32 v121, v118
	v_mov_b32_e32 v118, v106
	v_mul_f32_e32 v106, v111, v122
	v_exp_f32_e32 v106, v106
	v_pk_mul_f32 v[120:121], v[118:119], v[120:121]
	v_mov_b32_e32 v118, v107
	v_mul_f32_e32 v110, v120, v121
	v_add_f32_e32 v106, 1.0, v106
	v_rcp_f32_e32 v121, v106
	v_mov_b32_e32 v120, v111
	v_pk_mul_f32 v[106:107], v[118:119], v[120:121]
	s_nop 0
	v_mul_f32_e32 v111, v106, v107
	v_mul_f32_e32 v106, v112, v122
	v_exp_f32_e32 v106, v106
	v_mov_b32_e32 v118, v108
	v_add_f32_e32 v106, 1.0, v106
	v_rcp_f32_e32 v107, v106
	v_mov_b32_e32 v106, v112
	v_pk_mul_f32 v[106:107], v[118:119], v[106:107]
	s_nop 0
	v_mul_f32_e32 v108, v106, v107
	v_mul_f32_e32 v106, v113, v122
	v_exp_f32_e32 v106, v106
	v_mov_b32_e32 v118, v109
	v_add_f32_e32 v106, 1.0, v106
	v_rcp_f32_e32 v107, v106
	v_mov_b32_e32 v106, v113
	v_pk_mul_f32 v[106:107], v[118:119], v[106:107]
	s_nop 0
	v_mul_f32_e32 v109, v106, v107
	v_mul_f32_e32 v106, v102, v122
	v_exp_f32_e32 v106, v106
	v_mov_b32_e32 v118, v98
	v_mul_f32_e32 v98, v103, v122
	v_exp_f32_e32 v98, v98
	v_add_f32_e32 v106, 1.0, v106
	v_rcp_f32_e32 v107, v106
	v_mov_b32_e32 v106, v102
	v_add_f32_e32 v98, 1.0, v98
	v_pk_mul_f32 v[106:107], v[118:119], v[106:107]
	s_nop 0
	v_mul_f32_e32 v112, v106, v107
	v_rcp_f32_e32 v107, v98
	v_mov_b32_e32 v118, v99
	v_mov_b32_e32 v106, v103
	v_lshl_add_u64 v[102:103], v[116:117], 0, v[114:115]
	v_pk_mul_f32 v[98:99], v[118:119], v[106:107]
	v_mov_b32_e32 v118, v100
	v_mul_f32_e32 v106, v98, v99
; __device__ __forceinline__ unsigned pk2(float lo, float hi) { unsigned r; asm volatile("v_cvt_pk_bf16_f32 %0, %1, %2" : "=v"(r) : "v"(lo), "v"(hi)); return r; }
;     __device__ __forceinline__ void operator()(const f32x4 (&acc)[2][2][4][2], const Unit& u, int wr, int wc, int fr, int fq) const {
;     ...
;             for (int m = 0; m < 4; ++m) { bf16_t* rowp = O + (size_t)(row0 + ai * HALF + m * 16) * DFF + col0; const float rsv = rsqrtf(rs[ai][m] * (1.f / D) + EPS);
;                 const float rs2 = rsv * rsv, nrs = -1.4426950409f * rsv;
;                 float v[8];
; #pragma unroll
;                 for (int n = 0; n < 2; ++n)
; #pragma unroll
;                     for (int j = 0; j < 4; ++j) {
;                         const float g0 = acc[ai][0][m][n][j], u0 = acc[ai][1][m][n][j];
;                         v[n * 4 + j] = (g0 * u0) * (rs2 * __builtin_amdgcn_rcpf(1.0f + __builtin_amdgcn_exp2f(g0 * nrs))); }
;                 u32x4 w; w.x = pk2(v[0], v[1]); w.y = pk2(v[2], v[3]); w.z = pk2(v[4], v[5]); w.w = pk2(v[6], v[7]);
;                 *(u32x4*)rowp = w; }
	v_mul_f32_e32 v98, v104, v122
	v_exp_f32_e32 v98, v98
	s_nop 0
	v_add_f32_e32 v98, 1.0, v98
	v_rcp_f32_e32 v99, v98
	v_mov_b32_e32 v98, v104
	v_pk_mul_f32 v[98:99], v[118:119], v[98:99]
	s_nop 0
	v_mul_f32_e32 v104, v98, v99
	v_mul_f32_e32 v98, v105, v122
	v_exp_f32_e32 v98, v98
	v_mov_b32_e32 v118, v101
	v_add_f32_e32 v98, 1.0, v98
	v_rcp_f32_e32 v99, v98
	v_mov_b32_e32 v98, v105
	v_pk_mul_f32 v[98:99], v[118:119], v[98:99]
	s_nop 0
	v_mul_f32_e32 v101, v98, v99
	v_cvt_pk_bf16_f32 v98, v110, v111
	v_cvt_pk_bf16_f32 v99, v108, v109
	v_cvt_pk_bf16_f32 v100, v112, v106
	v_cvt_pk_bf16_f32 v101, v104, v101
	flat_store_dwordx4 v[102:103], v[98:101]
	v_mov_b32_e32 v102, v94
	s_nop 0
	v_fmamk_f32 v100, v162, 0x3a000000, v223
	v_cmp_gt_f32_e32 vcc, s29, v100
	v_mul_f32_e32 v101, 0x4b800000, v100
	v_mad_i64_i32 v[98:99], s[2:3], v163, s34, v[140:141]
	v_cndmask_b32_e32 v100, v100, v101, vcc
	v_rsq_f32_e32 v100, v100
	s_nop 0
	v_mul_f32_e32 v101, 0x45800000, v100
	v_cndmask_b32_e32 v100, v100, v101, vcc
	v_mul_f32_e32 v104, 0xbfb8aa3b, v100
	v_mul_f32_e32 v101, v100, v100
	v_mul_f32_e32 v100, v94, v104
	v_exp_f32_e32 v100, v100
	s_nop 0
	v_add_f32_e32 v100, 1.0, v100
	v_rcp_f32_e32 v103, v100
	v_mov_b32_e32 v100, v90
	v_mul_f32_e32 v90, v95, v104
	v_exp_f32_e32 v90, v90
	v_pk_mul_f32 v[102:103], v[100:101], v[102:103]
	v_mov_b32_e32 v100, v91
	v_mul_f32_e32 v94, v102, v103
	v_add_f32_e32 v90, 1.0, v90
	v_rcp_f32_e32 v103, v90
	v_mov_b32_e32 v102, v95
	v_pk_mul_f32 v[90:91], v[100:101], v[102:103]
	s_nop 0
	v_mul_f32_e32 v95, v90, v91
	v_mul_f32_e32 v90, v96, v104
	v_exp_f32_e32 v90, v90
	v_mov_b32_e32 v100, v92
	v_add_f32_e32 v90, 1.0, v90
	v_rcp_f32_e32 v91, v90
	v_mov_b32_e32 v90, v96
	v_pk_mul_f32 v[90:91], v[100:101], v[90:91]
	s_nop 0
	v_mul_f32_e32 v92, v90, v91
	v_mul_f32_e32 v90, v97, v104
	v_exp_f32_e32 v90, v90
	v_mov_b32_e32 v100, v93
	v_add_f32_e32 v90, 1.0, v90
	v_rcp_f32_e32 v91, v90
	v_mov_b32_e32 v90, v97
	v_pk_mul_f32 v[90:91], v[100:101], v[90:91]
	s_nop 0
	v_mul_f32_e32 v93, v90, v91
	v_mul_f32_e32 v90, v86, v104
	v_exp_f32_e32 v90, v90
	v_mov_b32_e32 v100, v82
	v_mul_f32_e32 v82, v87, v104
	v_exp_f32_e32 v82, v82
	v_add_f32_e32 v90, 1.0, v90
	v_rcp_f32_e32 v91, v90
	v_mov_b32_e32 v90, v86
	v_add_f32_e32 v82, 1.0, v82
	v_pk_mul_f32 v[90:91], v[100:101], v[90:91]
	s_nop 0
	v_mul_f32_e32 v96, v90, v91
	v_rcp_f32_e32 v91, v82
	v_mov_b32_e32 v100, v83
	v_mov_b32_e32 v90, v87
	v_lshl_add_u64 v[86:87], v[98:99], 0, v[114:115]
	v_pk_mul_f32 v[82:83], v[100:101], v[90:91]
	v_mov_b32_e32 v100, v84
	v_mul_f32_e32 v90, v82, v83
	v_mul_f32_e32 v82, v88, v104
	v_exp_f32_e32 v82, v82
	s_nop 0
	v_add_f32_e32 v82, 1.0, v82
	v_rcp_f32_e32 v83, v82
	v_mov_b32_e32 v82, v88
	v_pk_mul_f32 v[82:83], v[100:101], v[82:83]
	s_nop 0
	v_mul_f32_e32 v88, v82, v83
	v_mul_f32_e32 v82, v89, v104
	v_exp_f32_e32 v82, v82
	v_mov_b32_e32 v100, v85
	v_add_f32_e32 v82, 1.0, v82
	v_rcp_f32_e32 v83, v82
	v_mov_b32_e32 v82, v89
	v_pk_mul_f32 v[82:83], v[100:101], v[82:83]
	s_nop 0
	v_mul_f32_e32 v85, v82, v83
	v_cvt_pk_bf16_f32 v82, v94, v95
	v_cvt_pk_bf16_f32 v83, v92, v93
	v_cvt_pk_bf16_f32 v84, v96, v90
	v_cvt_pk_bf16_f32 v85, v88, v85
	flat_store_dwordx4 v[86:87], v[82:85]
	v_mov_b32_e32 v86, v78
	s_nop 0
	v_fmamk_f32 v84, v160, 0x3a000000, v223
	v_cmp_gt_f32_e32 vcc, s29, v84
	v_mul_f32_e32 v85, 0x4b800000, v84
	v_mad_i64_i32 v[82:83], s[2:3], v161, s34, v[140:141]
	v_cndmask_b32_e32 v84, v84, v85, vcc
	v_rsq_f32_e32 v84, v84
	s_nop 0
	v_mul_f32_e32 v85, 0x45800000, v84
	v_cndmask_b32_e32 v84, v84, v85, vcc
	v_mul_f32_e32 v88, 0xbfb8aa3b, v84
	v_mul_f32_e32 v85, v84, v84
	v_mul_f32_e32 v84, v78, v88
	v_exp_f32_e32 v84, v84
	s_nop 0
	v_add_f32_e32 v84, 1.0, v84
	v_rcp_f32_e32 v87, v84
	v_mov_b32_e32 v84, v74
	v_mul_f32_e32 v74, v79, v88
	v_exp_f32_e32 v74, v74
	v_pk_mul_f32 v[86:87], v[84:85], v[86:87]
	v_mov_b32_e32 v84, v75
	v_mul_f32_e32 v78, v86, v87
	v_add_f32_e32 v74, 1.0, v74
	v_rcp_f32_e32 v87, v74
	v_mov_b32_e32 v86, v79
	v_pk_mul_f32 v[74:75], v[84:85], v[86:87]
	s_nop 0
	v_mul_f32_e32 v79, v74, v75
	v_mul_f32_e32 v74, v80, v88
	v_exp_f32_e32 v74, v74
	v_mov_b32_e32 v84, v76
	v_add_f32_e32 v74, 1.0, v74
	v_rcp_f32_e32 v75, v74
	v_mov_b32_e32 v74, v80
	v_pk_mul_f32 v[74:75], v[84:85], v[74:75]
	s_nop 0
	v_mul_f32_e32 v76, v74, v75
	v_mul_f32_e32 v74, v81, v88
	v_exp_f32_e32 v74, v74
	v_mov_b32_e32 v84, v77
	v_add_f32_e32 v74, 1.0, v74
	v_rcp_f32_e32 v75, v74
	v_mov_b32_e32 v74, v81
	v_pk_mul_f32 v[74:75], v[84:85], v[74:75]
	s_nop 0
	v_mul_f32_e32 v77, v74, v75
	v_mul_f32_e32 v74, v70, v88
	v_exp_f32_e32 v74, v74
	v_mov_b32_e32 v84, v66
	v_mul_f32_e32 v66, v71, v88
	v_exp_f32_e32 v66, v66
	v_add_f32_e32 v74, 1.0, v74
	v_rcp_f32_e32 v75, v74
	v_mov_b32_e32 v74, v70
	v_add_f32_e32 v66, 1.0, v66
	v_pk_mul_f32 v[74:75], v[84:85], v[74:75]
	s_nop 0
	v_mul_f32_e32 v80, v74, v75
	v_rcp_f32_e32 v75, v66
	v_mov_b32_e32 v84, v67
	v_mov_b32_e32 v74, v71
	v_lshl_add_u64 v[70:71], v[82:83], 0, v[114:115]
	v_pk_mul_f32 v[66:67], v[84:85], v[74:75]
	v_mov_b32_e32 v84, v68
	v_mul_f32_e32 v74, v66, v67
	v_mul_f32_e32 v66, v72, v88
	v_exp_f32_e32 v66, v66
	s_nop 0
	v_add_f32_e32 v66, 1.0, v66
	v_rcp_f32_e32 v67, v66
	v_mov_b32_e32 v66, v72
	v_pk_mul_f32 v[66:67], v[84:85], v[66:67]
	s_nop 0
	v_mul_f32_e32 v72, v66, v67
	v_mul_f32_e32 v66, v73, v88
	v_exp_f32_e32 v66, v66
	v_mov_b32_e32 v84, v69
	v_add_f32_e32 v66, 1.0, v66
	v_rcp_f32_e32 v67, v66
	v_mov_b32_e32 v66, v73
	v_pk_mul_f32 v[66:67], v[84:85], v[66:67]
	s_nop 0
	v_mul_f32_e32 v69, v66, v67
	v_cvt_pk_bf16_f32 v66, v78, v79
	v_cvt_pk_bf16_f32 v67, v76, v77
	v_cvt_pk_bf16_f32 v68, v80, v74
	v_cvt_pk_bf16_f32 v69, v72, v69
; __device__ __forceinline__ unsigned pk2(float lo, float hi) { unsigned r; asm volatile("v_cvt_pk_bf16_f32 %0, %1, %2" : "=v"(r) : "v"(lo), "v"(hi)); return r; }
;     __device__ __forceinline__ void operator()(const f32x4 (&acc)[2][2][4][2], const Unit& u, int wr, int wc, int fr, int fq) const {
;     ...
;             for (int m = 0; m < 4; ++m) { bf16_t* rowp = O + (size_t)(row0 + ai * HALF + m * 16) * DFF + col0; const float rsv = rsqrtf(rs[ai][m] * (1.f / D) + EPS);
;                 const float rs2 = rsv * rsv, nrs = -1.4426950409f * rsv;
;                 float v[8];
; #pragma unroll
;                 for (int n = 0; n < 2; ++n)
; #pragma unroll
;                     for (int j = 0; j < 4; ++j) {
;                         const float g0 = acc[ai][0][m][n][j], u0 = acc[ai][1][m][n][j];
;                         v[n * 4 + j] = (g0 * u0) * (rs2 * __builtin_amdgcn_rcpf(1.0f + __builtin_amdgcn_exp2f(g0 * nrs))); }
;                 u32x4 w; w.x = pk2(v[0], v[1]); w.y = pk2(v[2], v[3]); w.z = pk2(v[4], v[5]); w.w = pk2(v[6], v[7]);
;                 *(u32x4*)rowp = w; }
	flat_store_dwordx4 v[70:71], v[66:69]
	v_mov_b32_e32 v70, v62
	s_nop 0
	v_fmamk_f32 v68, v158, 0x3a000000, v223
	v_cmp_gt_f32_e32 vcc, s29, v68
	v_mul_f32_e32 v69, 0x4b800000, v68
	v_mad_i64_i32 v[66:67], s[2:3], v159, s34, v[140:141]
	v_cndmask_b32_e32 v68, v68, v69, vcc
	v_rsq_f32_e32 v68, v68
	s_nop 0
	v_mul_f32_e32 v69, 0x45800000, v68
	v_cndmask_b32_e32 v68, v68, v69, vcc
	v_mul_f32_e32 v72, 0xbfb8aa3b, v68
	v_mul_f32_e32 v69, v68, v68
	v_mul_f32_e32 v68, v62, v72
	v_exp_f32_e32 v68, v68
	s_nop 0
	v_add_f32_e32 v68, 1.0, v68
	v_rcp_f32_e32 v71, v68
	v_mov_b32_e32 v68, v58
	v_mul_f32_e32 v58, v63, v72
	v_exp_f32_e32 v58, v58
	v_pk_mul_f32 v[70:71], v[68:69], v[70:71]
	v_mov_b32_e32 v68, v59
	v_mul_f32_e32 v62, v70, v71
	v_add_f32_e32 v58, 1.0, v58
	v_rcp_f32_e32 v71, v58
	v_mov_b32_e32 v70, v63
	v_pk_mul_f32 v[58:59], v[68:69], v[70:71]
	s_nop 0
	v_mul_f32_e32 v63, v58, v59
	v_mul_f32_e32 v58, v64, v72
	v_exp_f32_e32 v58, v58
	v_mov_b32_e32 v68, v60
	v_add_f32_e32 v58, 1.0, v58
	v_rcp_f32_e32 v59, v58
	v_mov_b32_e32 v58, v64
	v_pk_mul_f32 v[58:59], v[68:69], v[58:59]
	s_nop 0
	v_mul_f32_e32 v60, v58, v59
	v_mul_f32_e32 v58, v65, v72
	v_exp_f32_e32 v58, v58
	v_mov_b32_e32 v68, v61
	v_add_f32_e32 v58, 1.0, v58
	v_rcp_f32_e32 v59, v58
	v_mov_b32_e32 v58, v65
	v_pk_mul_f32 v[58:59], v[68:69], v[58:59]
	s_nop 0
	v_mul_f32_e32 v61, v58, v59
	v_mul_f32_e32 v58, v54, v72
	v_exp_f32_e32 v58, v58
	v_mov_b32_e32 v68, v50
	v_mul_f32_e32 v50, v55, v72
	v_exp_f32_e32 v50, v50
	v_add_f32_e32 v58, 1.0, v58
	v_rcp_f32_e32 v59, v58
	v_mov_b32_e32 v58, v54
	v_add_f32_e32 v50, 1.0, v50
	v_pk_mul_f32 v[58:59], v[68:69], v[58:59]
	s_nop 0
	v_mul_f32_e32 v64, v58, v59
	v_rcp_f32_e32 v59, v50
	v_mov_b32_e32 v68, v51
	v_mov_b32_e32 v58, v55
	v_lshl_add_u64 v[54:55], v[66:67], 0, v[114:115]
	v_pk_mul_f32 v[50:51], v[68:69], v[58:59]
	v_mov_b32_e32 v68, v52
	v_mul_f32_e32 v58, v50, v51
	v_mul_f32_e32 v50, v56, v72
	v_exp_f32_e32 v50, v50
	s_nop 0
	v_add_f32_e32 v50, 1.0, v50
	v_rcp_f32_e32 v51, v50
	v_mov_b32_e32 v50, v56
	v_pk_mul_f32 v[50:51], v[68:69], v[50:51]
	s_nop 0
	v_mul_f32_e32 v56, v50, v51
	v_mul_f32_e32 v50, v57, v72
	v_exp_f32_e32 v50, v50
	v_mov_b32_e32 v68, v53
	v_add_f32_e32 v50, 1.0, v50
	v_rcp_f32_e32 v51, v50
	v_mov_b32_e32 v50, v57
	v_pk_mul_f32 v[50:51], v[68:69], v[50:51]
	s_nop 0
	v_mul_f32_e32 v53, v50, v51
	v_cvt_pk_bf16_f32 v50, v62, v63
	v_cvt_pk_bf16_f32 v51, v60, v61
	v_cvt_pk_bf16_f32 v52, v64, v58
	v_cvt_pk_bf16_f32 v53, v56, v53
	flat_store_dwordx4 v[54:55], v[50:53]
	v_mov_b32_e32 v54, v46
	s_nop 0
	v_fmamk_f32 v52, v156, 0x3a000000, v223
	v_cmp_gt_f32_e32 vcc, s29, v52
	v_mul_f32_e32 v53, 0x4b800000, v52
	v_mad_i64_i32 v[50:51], s[2:3], v157, s34, v[140:141]
	v_cndmask_b32_e32 v52, v52, v53, vcc
	v_rsq_f32_e32 v52, v52
	s_nop 0
	v_mul_f32_e32 v53, 0x45800000, v52
	v_cndmask_b32_e32 v52, v52, v53, vcc
	v_mul_f32_e32 v56, 0xbfb8aa3b, v52
	v_mul_f32_e32 v53, v52, v52
	v_mul_f32_e32 v52, v46, v56
	v_exp_f32_e32 v52, v52
	s_nop 0
	v_add_f32_e32 v52, 1.0, v52
	v_rcp_f32_e32 v55, v52
	v_mov_b32_e32 v52, v42
	v_mul_f32_e32 v42, v47, v56
	v_exp_f32_e32 v42, v42
	v_pk_mul_f32 v[54:55], v[52:53], v[54:55]
	v_mov_b32_e32 v52, v43
	v_mul_f32_e32 v46, v54, v55
	v_add_f32_e32 v42, 1.0, v42
	v_rcp_f32_e32 v55, v42
	v_mov_b32_e32 v54, v47
	v_pk_mul_f32 v[42:43], v[52:53], v[54:55]
	s_nop 0
	v_mul_f32_e32 v47, v42, v43
	v_mul_f32_e32 v42, v48, v56
	v_exp_f32_e32 v42, v42
	v_mov_b32_e32 v52, v44
	v_add_f32_e32 v42, 1.0, v42
	v_rcp_f32_e32 v43, v42
	v_mov_b32_e32 v42, v48
	v_pk_mul_f32 v[42:43], v[52:53], v[42:43]
	s_nop 0
	v_mul_f32_e32 v44, v42, v43
	v_mul_f32_e32 v42, v49, v56
	v_exp_f32_e32 v42, v42
	v_mov_b32_e32 v52, v45
	v_add_f32_e32 v42, 1.0, v42
	v_rcp_f32_e32 v43, v42
	v_mov_b32_e32 v42, v49
	v_pk_mul_f32 v[42:43], v[52:53], v[42:43]
	s_nop 0
	v_mul_f32_e32 v45, v42, v43
	v_mul_f32_e32 v42, v38, v56
	v_exp_f32_e32 v42, v42
	v_mov_b32_e32 v52, v34
	v_mul_f32_e32 v34, v39, v56
	v_exp_f32_e32 v34, v34
	v_add_f32_e32 v42, 1.0, v42
	v_rcp_f32_e32 v43, v42
	v_mov_b32_e32 v42, v38
	v_add_f32_e32 v34, 1.0, v34
	v_pk_mul_f32 v[42:43], v[52:53], v[42:43]
	s_nop 0
	v_mul_f32_e32 v48, v42, v43
	v_rcp_f32_e32 v43, v34
	v_mov_b32_e32 v52, v35
	v_mov_b32_e32 v42, v39
	v_lshl_add_u64 v[38:39], v[50:51], 0, v[114:115]
	v_pk_mul_f32 v[34:35], v[52:53], v[42:43]
	v_mov_b32_e32 v52, v36
	v_mul_f32_e32 v42, v34, v35
	v_mul_f32_e32 v34, v40, v56
	v_exp_f32_e32 v34, v34
	s_nop 0
	v_add_f32_e32 v34, 1.0, v34
	v_rcp_f32_e32 v35, v34
	v_mov_b32_e32 v34, v40
	v_pk_mul_f32 v[34:35], v[52:53], v[34:35]
	s_nop 0
	v_mul_f32_e32 v40, v34, v35
	v_mul_f32_e32 v34, v41, v56
	v_exp_f32_e32 v34, v34
	v_mov_b32_e32 v52, v37
	v_add_f32_e32 v34, 1.0, v34
	v_rcp_f32_e32 v35, v34
	v_mov_b32_e32 v34, v41
	v_pk_mul_f32 v[34:35], v[52:53], v[34:35]
	s_nop 0
	v_mul_f32_e32 v37, v34, v35
	v_cvt_pk_bf16_f32 v34, v46, v47
	v_cvt_pk_bf16_f32 v35, v44, v45
	v_cvt_pk_bf16_f32 v36, v48, v42
	v_cvt_pk_bf16_f32 v37, v40, v37
	flat_store_dwordx4 v[38:39], v[34:37]
	v_mov_b32_e32 v38, v30
	s_nop 0
	v_fmamk_f32 v36, v154, 0x3a000000, v223
	v_cmp_gt_f32_e32 vcc, s29, v36
; __device__ __forceinline__ unsigned pk2(float lo, float hi) { unsigned r; asm volatile("v_cvt_pk_bf16_f32 %0, %1, %2" : "=v"(r) : "v"(lo), "v"(hi)); return r; }
; #define PG8_BAR __builtin_amdgcn_s_barrier()
; template <class Epi, class Sched, bool ALIGN_EPI = false, bool SP2 = false>
; __device__ __forceinline__ void gemm_phase(PG8_LAS unsigned char* lds, const Gemm g, const Sched& S, const Epi& E) {
;     ...
;         cur = nxt; cA = nA; cB = nB; ++ui;
;         if constexpr (ALIGN_EPI) { if (wr == 1) PG8_BAR; }
;     __device__ __forceinline__ void operator()(const f32x4 (&acc)[2][2][4][2], const Unit& u, int wr, int wc, int fr, int fq) const {
;     ...
;             for (int m = 0; m < 4; ++m) { bf16_t* rowp = O + (size_t)(row0 + ai * HALF + m * 16) * DFF + col0; const float rsv = rsqrtf(rs[ai][m] * (1.f / D) + EPS);
;                 const float rs2 = rsv * rsv, nrs = -1.4426950409f * rsv;
;                 float v[8];
; #pragma unroll
;                 for (int n = 0; n < 2; ++n)
; #pragma unroll
;                     for (int j = 0; j < 4; ++j) {
;                         const float g0 = acc[ai][0][m][n][j], u0 = acc[ai][1][m][n][j];
;                         v[n * 4 + j] = (g0 * u0) * (rs2 * __builtin_amdgcn_rcpf(1.0f + __builtin_amdgcn_exp2f(g0 * nrs))); }
;                 u32x4 w; w.x = pk2(v[0], v[1]); w.y = pk2(v[2], v[3]); w.z = pk2(v[4], v[5]); w.w = pk2(v[6], v[7]);
;                 *(u32x4*)rowp = w; }
	v_mul_f32_e32 v37, 0x4b800000, v36
	v_mad_i64_i32 v[34:35], s[2:3], v155, s34, v[140:141]
	v_cndmask_b32_e32 v36, v36, v37, vcc
	v_rsq_f32_e32 v36, v36
	s_nop 0
	v_mul_f32_e32 v37, 0x45800000, v36
	v_cndmask_b32_e32 v36, v36, v37, vcc
	v_mul_f32_e32 v40, 0xbfb8aa3b, v36
	v_mul_f32_e32 v37, v36, v36
	v_mul_f32_e32 v36, v30, v40
	v_exp_f32_e32 v36, v36
	s_nop 0
	v_add_f32_e32 v36, 1.0, v36
	v_rcp_f32_e32 v39, v36
	v_mov_b32_e32 v36, v26
	v_mul_f32_e32 v26, v31, v40
	v_exp_f32_e32 v26, v26
	v_pk_mul_f32 v[38:39], v[36:37], v[38:39]
	v_mov_b32_e32 v36, v27
	v_mul_f32_e32 v30, v38, v39
	v_add_f32_e32 v26, 1.0, v26
	v_rcp_f32_e32 v39, v26
	v_mov_b32_e32 v38, v31
	v_pk_mul_f32 v[26:27], v[36:37], v[38:39]
	s_nop 0
	v_mul_f32_e32 v31, v26, v27
	v_mul_f32_e32 v26, v32, v40
	v_exp_f32_e32 v26, v26
	v_mov_b32_e32 v36, v28
	v_add_f32_e32 v26, 1.0, v26
	v_rcp_f32_e32 v27, v26
	v_mov_b32_e32 v26, v32
	v_pk_mul_f32 v[26:27], v[36:37], v[26:27]
	s_nop 0
	v_mul_f32_e32 v28, v26, v27
	v_mul_f32_e32 v26, v33, v40
	v_exp_f32_e32 v26, v26
	v_mov_b32_e32 v36, v29
	v_add_f32_e32 v26, 1.0, v26
	v_rcp_f32_e32 v27, v26
	v_mov_b32_e32 v26, v33
	v_pk_mul_f32 v[26:27], v[36:37], v[26:27]
	s_nop 0
	v_mul_f32_e32 v29, v26, v27
	v_mul_f32_e32 v26, v22, v40
	v_exp_f32_e32 v26, v26
	v_mov_b32_e32 v36, v18
	v_mul_f32_e32 v18, v23, v40
	v_exp_f32_e32 v18, v18
	v_add_f32_e32 v26, 1.0, v26
	v_rcp_f32_e32 v27, v26
	v_mov_b32_e32 v26, v22
	v_add_f32_e32 v18, 1.0, v18
	v_pk_mul_f32 v[26:27], v[36:37], v[26:27]
	s_nop 0
	v_mul_f32_e32 v32, v26, v27
	v_rcp_f32_e32 v27, v18
	v_mov_b32_e32 v36, v19
	v_mov_b32_e32 v26, v23
	v_lshl_add_u64 v[22:23], v[34:35], 0, v[114:115]
	v_pk_mul_f32 v[18:19], v[36:37], v[26:27]
	v_mov_b32_e32 v36, v20
	v_mul_f32_e32 v26, v18, v19
	v_mul_f32_e32 v18, v24, v40
	v_exp_f32_e32 v18, v18
	s_nop 0
	v_add_f32_e32 v18, 1.0, v18
	v_rcp_f32_e32 v19, v18
	v_mov_b32_e32 v18, v24
	v_pk_mul_f32 v[18:19], v[36:37], v[18:19]
	s_nop 0
	v_mul_f32_e32 v24, v18, v19
	v_mul_f32_e32 v18, v25, v40
	v_exp_f32_e32 v18, v18
	v_mov_b32_e32 v36, v21
	v_add_f32_e32 v18, 1.0, v18
	v_rcp_f32_e32 v19, v18
	v_mov_b32_e32 v18, v25
	v_pk_mul_f32 v[18:19], v[36:37], v[18:19]
	s_nop 0
	v_mul_f32_e32 v21, v18, v19
	v_cvt_pk_bf16_f32 v18, v30, v31
	v_cvt_pk_bf16_f32 v19, v28, v29
	v_cvt_pk_bf16_f32 v20, v32, v26
	v_cvt_pk_bf16_f32 v21, v24, v21
	flat_store_dwordx4 v[22:23], v[18:21]
	v_mov_b32_e32 v22, v14
	s_nop 0
	v_fmamk_f32 v20, v152, 0x3a000000, v223
	v_cmp_gt_f32_e32 vcc, s29, v20
	v_mul_f32_e32 v21, 0x4b800000, v20
	v_mad_i64_i32 v[18:19], s[2:3], v153, s34, v[140:141]
	v_cndmask_b32_e32 v20, v20, v21, vcc
	v_rsq_f32_e32 v20, v20
	s_nop 0
	v_mul_f32_e32 v21, 0x45800000, v20
	v_cndmask_b32_e32 v20, v20, v21, vcc
	v_mul_f32_e32 v24, 0xbfb8aa3b, v20
	v_mul_f32_e32 v21, v20, v20
	v_mul_f32_e32 v20, v14, v24
	v_exp_f32_e32 v20, v20
	s_andn2_b64 vcc, exec, s[40:41]
	v_add_f32_e32 v20, 1.0, v20
	v_rcp_f32_e32 v23, v20
	v_mov_b32_e32 v20, v10
	v_mul_f32_e32 v10, v15, v24
	v_exp_f32_e32 v10, v10
	v_pk_mul_f32 v[22:23], v[20:21], v[22:23]
	v_mov_b32_e32 v20, v11
	v_mul_f32_e32 v14, v22, v23
	v_add_f32_e32 v10, 1.0, v10
	v_rcp_f32_e32 v23, v10
	v_mov_b32_e32 v22, v15
	v_pk_mul_f32 v[10:11], v[20:21], v[22:23]
	s_nop 0
	v_mul_f32_e32 v15, v10, v11
	v_mul_f32_e32 v10, v16, v24
	v_exp_f32_e32 v10, v10
	v_mov_b32_e32 v20, v12
	v_add_f32_e32 v10, 1.0, v10
	v_rcp_f32_e32 v11, v10
	v_mov_b32_e32 v10, v16
	v_pk_mul_f32 v[10:11], v[20:21], v[10:11]
	s_nop 0
	v_mul_f32_e32 v12, v10, v11
	v_mul_f32_e32 v10, v17, v24
	v_exp_f32_e32 v10, v10
	v_mov_b32_e32 v20, v13
	v_add_f32_e32 v10, 1.0, v10
	v_rcp_f32_e32 v11, v10
	v_mov_b32_e32 v10, v17
	v_pk_mul_f32 v[10:11], v[20:21], v[10:11]
	s_nop 0
	v_mul_f32_e32 v13, v10, v11
	v_mul_f32_e32 v10, v6, v24
	v_exp_f32_e32 v10, v10
	v_mov_b32_e32 v20, v2
	v_mul_f32_e32 v2, v7, v24
	v_exp_f32_e32 v2, v2
	v_add_f32_e32 v10, 1.0, v10
	v_rcp_f32_e32 v11, v10
	v_mov_b32_e32 v10, v6
	v_add_f32_e32 v2, 1.0, v2
	v_pk_mul_f32 v[10:11], v[20:21], v[10:11]
	s_nop 0
	v_mul_f32_e32 v16, v10, v11
	v_rcp_f32_e32 v11, v2
	v_mov_b32_e32 v20, v3
	v_mov_b32_e32 v10, v7
	v_lshl_add_u64 v[6:7], v[18:19], 0, v[114:115]
	v_pk_mul_f32 v[2:3], v[20:21], v[10:11]
	v_mov_b32_e32 v20, v4
	v_mul_f32_e32 v10, v2, v3
	v_mul_f32_e32 v2, v8, v24
	v_exp_f32_e32 v2, v2
	s_nop 0
	v_add_f32_e32 v2, 1.0, v2
	v_rcp_f32_e32 v3, v2
	v_mov_b32_e32 v2, v8
	v_pk_mul_f32 v[2:3], v[20:21], v[2:3]
	s_nop 0
	v_mul_f32_e32 v8, v2, v3
	v_mul_f32_e32 v2, v9, v24
	v_exp_f32_e32 v2, v2
	v_mov_b32_e32 v20, v5
	v_add_f32_e32 v2, 1.0, v2
	v_rcp_f32_e32 v3, v2
	v_mov_b32_e32 v2, v9
	v_pk_mul_f32 v[2:3], v[20:21], v[2:3]
	s_nop 0
	v_mul_f32_e32 v5, v2, v3
	v_cvt_pk_bf16_f32 v2, v14, v15
	v_cvt_pk_bf16_f32 v3, v12, v13
	v_cvt_pk_bf16_f32 v4, v16, v10
	v_cvt_pk_bf16_f32 v5, v8, v5
	flat_store_dwordx4 v[6:7], v[2:5]
	s_cbranch_vccnz .LBB0_1483
	s_andn2_b64 vcc, exec, s[14:15]
	s_cbranch_vccnz .LBB0_1482
	s_barrier
	s_branch .LBB0_1482
	s_nop 0
	s_nop 0
	s_nop 0
	s_nop 0
	s_nop 0
	s_nop 0
	s_nop 0
	s_nop 0
	s_nop 0
	s_nop 0
	s_nop 0
	s_nop 0
	s_nop 0
	s_nop 0
	s_nop 0
	s_nop 0

; #define PG8_STAGE(bufoff, gbase, voff) do { _Pragma("unroll") for (int _i = 0; _i < 2; ++_i) \
;         __builtin_amdgcn_global_load_lds((const unsigned*)((const char*)(gbase) + (voff)[_i]), (PG8_LAS unsigned*)(lds + (bufoff) + ldsw + _i * 8192), 16, 0, 0); } while (0)
; #define PG8_LDA(dst, b, h) do { _Pragma("unroll") for (int m = 0; m < 4; ++m) _Pragma("unroll") for (int k = 0; k < 2; ++k) dst[m][k] = *(const PG8_LAS bf16x8*)(lds + PG8_SA(b, h) + aoff + m * 2048 + k * 1024); } while (0)
; #define PG8_LDB(dst, b, h) do { _Pragma("unroll") for (int n = 0; n < 2; ++n) _Pragma("unroll") for (int k = 0; k < 2; ++k) dst[n][k] = *(const PG8_LAS bf16x8*)(lds + PG8_SB(b, h) + boff + n * 2048 + k * 1024); } while (0)
; #define PG8_WAIT_V(n) asm volatile("s_waitcnt vmcnt(" #n ")" ::: "memory")
; #define PG8_WAIT_L(n) asm volatile("s_waitcnt lgkmcnt(" #n ")" ::: "memory")
; #define PG8_BAR __builtin_amdgcn_s_barrier()
; template <class Epi, class Sched, bool ALIGN_EPI = false, bool SP2 = false>
; __device__ __forceinline__ void gemm_phase(PG8_LAS unsigned char* lds, const Gemm g, const Sched& S, const Epi& E) {
;     ...
;         const bool has_next = S.next(ui + 1, nxt);
;         const char* nA = has_next ? (const char*)g.A + (size_t)nxt.pm * tstep + (size_t)nxt.kt0 * kstep : cA; const char* nB = has_next ? (const char*)g.Bt + (size_t)nxt.pn * tstep + (size_t)nxt.kt0 * kstep : cB;
;         const int nt = cur.nkt;
;         for (int t = 0; t < nt; t += 2) {
;             const bool last = (t == nt - 2);
;             const char* a1 = cA + (size_t)(t + 1) * kstep;
;             const char* a2 = last ? nA : cA + (size_t)(t + 2) * kstep; const char* b2 = last ? nB : cB + (size_t)(t + 2) * kstep;
;             const char* a3 = a2 + kstep; const char* b3 = b2 + kstep;
;             if (last && has_next) S.a_ready(nxt);
;             if constexpr (SP2) {
;             PG8_LDB(B0, 0, 0); PG8_LDB(B1, 0, 1); PG8_SCHED; PG8_LDA(At, 0, 0); PG8_STAGE(PG8_SA(1, 1), a1 + hstep, voffA);
;             PG8_WAIT_V(8); PG8_WAIT_L(0); PG8_BAR; PG8_MMA(0, 0, At, B0); PG8_MMA(0, 1, At, B1); PG8_BAR; PG8_SCHED;
;             PG8_LDA(At, 0, 1); PG8_STAGE(PG8_SB(0, 0), b2, voffB); PG8_STAGE(PG8_SB(0, 1), b2 + hstep, voffB); PG8_STAGE(PG8_SA(0, 0), a2, voffA);
;             PG8_WAIT_V(8); PG8_WAIT_L(0); PG8_BAR; PG8_MMA(1, 0, At, B0); PG8_MMA(1, 1, At, B1); PG8_BAR; PG8_SCHED;
.Lmy_p8_prio_done:
.LBB0_1588:
	s_add_i32 s3, s2, 2
	s_add_u32 s22, s46, 0x100
	s_addc_u32 s23, s47, 0
	s_add_i32 s88, 0, 0x10000
	s_cmp_eq_u32 s57, s2
	s_cselect_b32 s65, s59, s23
	s_cselect_b32 s64, s58, s22
	s_cselect_b32 s63, s61, s87
	s_cselect_b32 s62, s60, s86
	s_add_i32 s2, 0, 0x14000
	v_add_u32_e32 v142, s88, v232
	v_add_u32_e32 v158, s2, v232
	s_waitcnt lgkmcnt(0)
	ds_read_b128 v[130:133], v142
	ds_read_b128 v[134:137], v142 offset:1024
	ds_read_b128 v[138:141], v142 offset:2048
	ds_read_b128 v[142:145], v142 offset:3072
	ds_read_b128 v[146:149], v158
	ds_read_b128 v[150:153], v158 offset:1024
	ds_read_b128 v[154:157], v158 offset:2048
	ds_read_b128 v[158:161], v158 offset:3072
	v_lshl_add_u64 v[218:219], s[46:47], 0, v[208:209]
	s_add_i32 m0, s33, 0xc000
	ds_read_b128 v[162:165], v234
	ds_read_b128 v[166:169], v234 offset:1024
	ds_read_b128 v[170:173], v234 offset:2048
	ds_read_b128 v[174:177], v234 offset:3072
	ds_read_b128 v[178:181], v234 offset:4096
	ds_read_b128 v[182:185], v234 offset:5120
	ds_read_b128 v[210:213], v234 offset:6144
	ds_read_b128 v[214:217], v234 offset:7168
	global_load_lds_dwordx4 v[218:219], off
	v_lshl_add_u64 v[218:219], s[46:47], 0, v[206:207]
	s_add_i32 m0, s33, 0xe000
	s_nop 0
	global_load_lds_dwordx4 v[218:219], off
	s_waitcnt vmcnt(8)
	s_waitcnt lgkmcnt(0)
	s_barrier
	v_mfma_f32_16x16x32_bf16 v[126:129], v[130:133], v[162:165], v[126:129]
	v_mfma_f32_16x16x32_bf16 v[122:125], v[138:141], v[162:165], v[122:125]
	v_mfma_f32_16x16x32_bf16 v[118:121], v[130:133], v[170:173], v[118:121]
	v_mfma_f32_16x16x32_bf16 v[114:117], v[138:141], v[170:173], v[114:117]
	v_mfma_f32_16x16x32_bf16 v[106:109], v[130:133], v[178:181], v[106:109]
	v_mfma_f32_16x16x32_bf16 v[98:101], v[138:141], v[178:181], v[98:101]
	v_mfma_f32_16x16x32_bf16 v[90:93], v[130:133], v[210:213], v[90:93]
	v_mfma_f32_16x16x32_bf16 v[82:85], v[138:141], v[210:213], v[82:85]
	v_mfma_f32_16x16x32_bf16 v[126:129], v[134:137], v[166:169], v[126:129]
	v_mfma_f32_16x16x32_bf16 v[122:125], v[142:145], v[166:169], v[122:125]
	v_mfma_f32_16x16x32_bf16 v[118:121], v[134:137], v[174:177], v[118:121]
	v_mfma_f32_16x16x32_bf16 v[114:117], v[142:145], v[174:177], v[114:117]
	v_mfma_f32_16x16x32_bf16 v[106:109], v[134:137], v[182:185], v[106:109]
	v_mfma_f32_16x16x32_bf16 v[98:101], v[142:145], v[182:185], v[98:101]
	v_mfma_f32_16x16x32_bf16 v[90:93], v[134:137], v[214:217], v[90:93]
	v_mfma_f32_16x16x32_bf16 v[82:85], v[142:145], v[214:217], v[82:85]
	v_mfma_f32_16x16x32_bf16 v[110:113], v[146:149], v[162:165], v[110:113]
	v_mfma_f32_16x16x32_bf16 v[102:105], v[154:157], v[162:165], v[102:105]
	v_mfma_f32_16x16x32_bf16 v[94:97], v[146:149], v[170:173], v[94:97]
	v_mfma_f32_16x16x32_bf16 v[86:89], v[154:157], v[170:173], v[86:89]
	v_mfma_f32_16x16x32_bf16 v[78:81], v[146:149], v[178:181], v[78:81]
	v_mfma_f32_16x16x32_bf16 v[74:77], v[154:157], v[178:181], v[74:77]
	v_mfma_f32_16x16x32_bf16 v[70:73], v[146:149], v[210:213], v[70:73]
	v_mfma_f32_16x16x32_bf16 v[66:69], v[154:157], v[210:213], v[66:69]
	v_mfma_f32_16x16x32_bf16 v[110:113], v[150:153], v[166:169], v[110:113]
	v_mfma_f32_16x16x32_bf16 v[102:105], v[158:161], v[166:169], v[102:105]
	v_mfma_f32_16x16x32_bf16 v[94:97], v[150:153], v[174:177], v[94:97]
	v_mfma_f32_16x16x32_bf16 v[86:89], v[158:161], v[174:177], v[86:89]
	v_mfma_f32_16x16x32_bf16 v[78:81], v[150:153], v[182:185], v[78:81]
	v_mfma_f32_16x16x32_bf16 v[74:77], v[158:161], v[182:185], v[74:77]
	v_mfma_f32_16x16x32_bf16 v[70:73], v[150:153], v[214:217], v[70:73]
	v_mfma_f32_16x16x32_bf16 v[66:69], v[158:161], v[214:217], v[66:69]
	s_barrier
	s_add_i32 s46, s88, s28
	v_lshl_add_u64 v[218:219], s[62:63], 0, v[0:1]
	s_mov_b32 m0, s46
	ds_read_b128 v[162:165], v234 offset:16384
	ds_read_b128 v[166:169], v234 offset:17408
	ds_read_b128 v[170:173], v234 offset:18432
	ds_read_b128 v[174:177], v234 offset:19456
	ds_read_b128 v[178:181], v234 offset:20480
	ds_read_b128 v[182:185], v234 offset:21504
	ds_read_b128 v[210:213], v234 offset:22528
	ds_read_b128 v[214:217], v234 offset:23552
	global_load_lds_dwordx4 v[218:219], off
	s_add_i32 m0, s46, 0x2000
	s_add_u32 s46, s62, 0x160000
	v_lshl_add_u64 v[236:237], s[62:63], 0, v[204:205]
	s_addc_u32 s47, s63, 0
	s_add_i32 s2, s2, s28
	global_load_lds_dwordx4 v[236:237], off
	v_lshl_add_u64 v[238:239], s[46:47], 0, v[0:1]
	s_mov_b32 m0, s2
	v_lshl_add_u64 v[240:241], s[64:65], 0, v[202:203]
	global_load_lds_dwordx4 v[238:239], off
	v_lshl_add_u64 v[238:239], s[46:47], 0, v[204:205]
	s_add_i32 m0, s2, 0x2000
	s_nop 0
	global_load_lds_dwordx4 v[238:239], off
	v_lshl_add_u64 v[238:239], s[64:65], 0, v[200:201]
	s_mov_b32 m0, s33
	s_nop 0
	global_load_lds_dwordx4 v[238:239], off
	s_mov_b32 m0, s35
	s_nop 0
	global_load_lds_dwordx4 v[240:241], off
	s_waitcnt vmcnt(8)
	s_waitcnt lgkmcnt(0)
	s_barrier
; #define PG8_STAGE(bufoff, gbase, voff) do { _Pragma("unroll") for (int _i = 0; _i < 2; ++_i) \
;         __builtin_amdgcn_global_load_lds((const unsigned*)((const char*)(gbase) + (voff)[_i]), (PG8_LAS unsigned*)(lds + (bufoff) + ldsw + _i * 8192), 16, 0, 0); } while (0)
; #define PG8_LDA(dst, b, h) do { _Pragma("unroll") for (int m = 0; m < 4; ++m) _Pragma("unroll") for (int k = 0; k < 2; ++k) dst[m][k] = *(const PG8_LAS bf16x8*)(lds + PG8_SA(b, h) + aoff + m * 2048 + k * 1024); } while (0)
; #define PG8_LDB(dst, b, h) do { _Pragma("unroll") for (int n = 0; n < 2; ++n) _Pragma("unroll") for (int k = 0; k < 2; ++k) dst[n][k] = *(const PG8_LAS bf16x8*)(lds + PG8_SB(b, h) + boff + n * 2048 + k * 1024); } while (0)
; #define PG8_MMA(ai, bj, At, Bt) do { __builtin_amdgcn_s_setprio(1); _Pragma("unroll") for (int m = 0; m < 4; ++m) _Pragma("unroll") for (int n = 0; n < 2; ++n) _Pragma("unroll") for (int k = 0; k < 2; ++k) \
;         acc[ai][bj][m][n] = __builtin_amdgcn_mfma_f32_16x16x32_bf16(Bt[n][k], At[m][k], acc[ai][bj][m][n], 0, 0, 0); __builtin_amdgcn_s_setprio(0); } while (0)
; #define PG8_WAIT_V(n) asm volatile("s_waitcnt vmcnt(" #n ")" ::: "memory")
; #define PG8_WAIT_L(n) asm volatile("s_waitcnt lgkmcnt(" #n ")" ::: "memory")
; #define PG8_BAR __builtin_amdgcn_s_barrier()
; #define PG8_SCHED __builtin_amdgcn_sched_barrier(0)
; template <class Epi, class Sched, bool ALIGN_EPI = false, bool SP2 = false>
; __device__ __forceinline__ void gemm_phase(PG8_LAS unsigned char* lds, const Gemm g, const Sched& S, const Epi& E) {
;     ...
;             PG8_WAIT_V(8); PG8_WAIT_L(0); PG8_BAR; PG8_MMA(1, 0, At, B0); PG8_MMA(1, 1, At, B1); PG8_BAR; PG8_SCHED;
;             PG8_LDB(B0, 1, 0); PG8_LDB(B1, 1, 1); PG8_SCHED; PG8_LDA(At, 1, 0); PG8_STAGE(PG8_SA(0, 1), a2 + hstep, voffA);
;             PG8_WAIT_V(8); PG8_WAIT_L(0); PG8_BAR; PG8_MMA(0, 0, At, B0); PG8_MMA(0, 1, At, B1); PG8_BAR; PG8_SCHED;
;             PG8_LDA(At, 1, 1); PG8_STAGE(PG8_SB(1, 0), b3, voffB); PG8_STAGE(PG8_SB(1, 1), b3 + hstep, voffB); PG8_STAGE(PG8_SA(1, 0), a3, voffA);
;             PG8_WAIT_V(8); PG8_WAIT_L(0); PG8_BAR; PG8_MMA(1, 0, At, B0); PG8_MMA(1, 1, At, B1); PG8_BAR; PG8_SCHED;
	v_mfma_f32_16x16x32_bf16 v[62:65], v[130:133], v[162:165], v[62:65]
	v_mfma_f32_16x16x32_bf16 v[58:61], v[138:141], v[162:165], v[58:61]
	v_mfma_f32_16x16x32_bf16 v[54:57], v[130:133], v[170:173], v[54:57]
	v_mfma_f32_16x16x32_bf16 v[50:53], v[138:141], v[170:173], v[50:53]
	v_mfma_f32_16x16x32_bf16 v[38:41], v[130:133], v[178:181], v[38:41]
	v_mfma_f32_16x16x32_bf16 v[34:37], v[138:141], v[178:181], v[34:37]
	v_mfma_f32_16x16x32_bf16 v[22:25], v[130:133], v[210:213], v[22:25]
	v_mfma_f32_16x16x32_bf16 v[18:21], v[138:141], v[210:213], v[18:21]
	v_mfma_f32_16x16x32_bf16 v[62:65], v[134:137], v[166:169], v[62:65]
	v_mfma_f32_16x16x32_bf16 v[58:61], v[142:145], v[166:169], v[58:61]
	v_mfma_f32_16x16x32_bf16 v[54:57], v[134:137], v[174:177], v[54:57]
	v_mfma_f32_16x16x32_bf16 v[50:53], v[142:145], v[174:177], v[50:53]
	v_mfma_f32_16x16x32_bf16 v[38:41], v[134:137], v[182:185], v[38:41]
	v_mfma_f32_16x16x32_bf16 v[34:37], v[142:145], v[182:185], v[34:37]
	v_mfma_f32_16x16x32_bf16 v[22:25], v[134:137], v[214:217], v[22:25]
	v_mfma_f32_16x16x32_bf16 v[18:21], v[142:145], v[214:217], v[18:21]
	v_mfma_f32_16x16x32_bf16 v[46:49], v[146:149], v[162:165], v[46:49]
	v_mfma_f32_16x16x32_bf16 v[42:45], v[154:157], v[162:165], v[42:45]
	v_mfma_f32_16x16x32_bf16 v[30:33], v[146:149], v[170:173], v[30:33]
	v_mfma_f32_16x16x32_bf16 v[26:29], v[154:157], v[170:173], v[26:29]
	v_mfma_f32_16x16x32_bf16 v[14:17], v[146:149], v[178:181], v[14:17]
	v_mfma_f32_16x16x32_bf16 v[10:13], v[154:157], v[178:181], v[10:13]
	v_mfma_f32_16x16x32_bf16 v[6:9], v[146:149], v[210:213], v[6:9]
	v_mfma_f32_16x16x32_bf16 v[2:5], v[154:157], v[210:213], v[2:5]
	v_mfma_f32_16x16x32_bf16 v[46:49], v[150:153], v[166:169], v[46:49]
	v_mfma_f32_16x16x32_bf16 v[42:45], v[158:161], v[166:169], v[42:45]
	v_mfma_f32_16x16x32_bf16 v[30:33], v[150:153], v[174:177], v[30:33]
	v_mfma_f32_16x16x32_bf16 v[26:29], v[158:161], v[174:177], v[26:29]
	v_mfma_f32_16x16x32_bf16 v[14:17], v[150:153], v[182:185], v[14:17]
	v_mfma_f32_16x16x32_bf16 v[10:13], v[158:161], v[182:185], v[10:13]
	v_mfma_f32_16x16x32_bf16 v[6:9], v[150:153], v[214:217], v[6:9]
	v_mfma_f32_16x16x32_bf16 v[2:5], v[158:161], v[214:217], v[2:5]
	s_barrier
	s_add_i32 s2, 0, 0x18000
	s_add_i32 s88, 0, 0x1c000
	v_add_u32_e32 v142, s2, v232
	v_add_u32_e32 v158, s88, v232
	ds_read_b128 v[130:133], v142
	ds_read_b128 v[134:137], v142 offset:1024
	ds_read_b128 v[138:141], v142 offset:2048
	ds_read_b128 v[142:145], v142 offset:3072
	ds_read_b128 v[146:149], v158
	ds_read_b128 v[150:153], v158 offset:1024
	ds_read_b128 v[154:157], v158 offset:2048
	ds_read_b128 v[158:161], v158 offset:3072
	s_add_u32 s46, s64, 0x160000
	s_addc_u32 s47, s65, 0
	s_mov_b32 m0, s36
	v_lshl_add_u64 v[242:243], s[46:47], 0, v[200:201]
	ds_read_b128 v[162:165], v234 offset:32768
	ds_read_b128 v[166:169], v234 offset:33792
	ds_read_b128 v[170:173], v234 offset:34816
	ds_read_b128 v[174:177], v234 offset:35840
	ds_read_b128 v[178:181], v234 offset:36864
	ds_read_b128 v[182:185], v234 offset:37888
	ds_read_b128 v[210:213], v234 offset:38912
	ds_read_b128 v[214:217], v234 offset:39936
	global_load_lds_dwordx4 v[242:243], off
	v_lshl_add_u64 v[242:243], s[46:47], 0, v[202:203]
	s_mov_b32 m0, s37
	s_nop 0
	global_load_lds_dwordx4 v[242:243], off
	s_waitcnt vmcnt(8)
	s_waitcnt lgkmcnt(0)
	s_barrier
	v_mfma_f32_16x16x32_bf16 v[126:129], v[130:133], v[162:165], v[126:129]
	v_mfma_f32_16x16x32_bf16 v[122:125], v[138:141], v[162:165], v[122:125]
	v_mfma_f32_16x16x32_bf16 v[118:121], v[130:133], v[170:173], v[118:121]
	v_mfma_f32_16x16x32_bf16 v[114:117], v[138:141], v[170:173], v[114:117]
	v_mfma_f32_16x16x32_bf16 v[106:109], v[130:133], v[178:181], v[106:109]
	v_mfma_f32_16x16x32_bf16 v[98:101], v[138:141], v[178:181], v[98:101]
	v_mfma_f32_16x16x32_bf16 v[90:93], v[130:133], v[210:213], v[90:93]
	v_mfma_f32_16x16x32_bf16 v[82:85], v[138:141], v[210:213], v[82:85]
	v_mfma_f32_16x16x32_bf16 v[126:129], v[134:137], v[166:169], v[126:129]
	v_mfma_f32_16x16x32_bf16 v[122:125], v[142:145], v[166:169], v[122:125]
	v_mfma_f32_16x16x32_bf16 v[118:121], v[134:137], v[174:177], v[118:121]
	v_mfma_f32_16x16x32_bf16 v[114:117], v[142:145], v[174:177], v[114:117]
	v_mfma_f32_16x16x32_bf16 v[106:109], v[134:137], v[182:185], v[106:109]
	v_mfma_f32_16x16x32_bf16 v[98:101], v[142:145], v[182:185], v[98:101]
	v_mfma_f32_16x16x32_bf16 v[90:93], v[134:137], v[214:217], v[90:93]
	v_mfma_f32_16x16x32_bf16 v[82:85], v[142:145], v[214:217], v[82:85]
	v_mfma_f32_16x16x32_bf16 v[110:113], v[146:149], v[162:165], v[110:113]
	v_mfma_f32_16x16x32_bf16 v[102:105], v[154:157], v[162:165], v[102:105]
	v_mfma_f32_16x16x32_bf16 v[94:97], v[146:149], v[170:173], v[94:97]
	v_mfma_f32_16x16x32_bf16 v[86:89], v[154:157], v[170:173], v[86:89]
	v_mfma_f32_16x16x32_bf16 v[78:81], v[146:149], v[178:181], v[78:81]
	v_mfma_f32_16x16x32_bf16 v[74:77], v[154:157], v[178:181], v[74:77]
	v_mfma_f32_16x16x32_bf16 v[70:73], v[146:149], v[210:213], v[70:73]
	v_mfma_f32_16x16x32_bf16 v[66:69], v[154:157], v[210:213], v[66:69]
	v_mfma_f32_16x16x32_bf16 v[110:113], v[150:153], v[166:169], v[110:113]
	v_mfma_f32_16x16x32_bf16 v[102:105], v[158:161], v[166:169], v[102:105]
	v_mfma_f32_16x16x32_bf16 v[94:97], v[150:153], v[174:177], v[94:97]
	v_mfma_f32_16x16x32_bf16 v[86:89], v[158:161], v[174:177], v[86:89]
	v_mfma_f32_16x16x32_bf16 v[78:81], v[150:153], v[182:185], v[78:81]
	v_mfma_f32_16x16x32_bf16 v[74:77], v[158:161], v[182:185], v[74:77]
	v_mfma_f32_16x16x32_bf16 v[70:73], v[150:153], v[214:217], v[70:73]
	v_mfma_f32_16x16x32_bf16 v[66:69], v[158:161], v[214:217], v[66:69]
	s_barrier
; #define PG8_STAGE(bufoff, gbase, voff) do { _Pragma("unroll") for (int _i = 0; _i < 2; ++_i) \
;         __builtin_amdgcn_global_load_lds((const unsigned*)((const char*)(gbase) + (voff)[_i]), (PG8_LAS unsigned*)(lds + (bufoff) + ldsw + _i * 8192), 16, 0, 0); } while (0)
; #define PG8_LDA(dst, b, h) do { _Pragma("unroll") for (int m = 0; m < 4; ++m) _Pragma("unroll") for (int k = 0; k < 2; ++k) dst[m][k] = *(const PG8_LAS bf16x8*)(lds + PG8_SA(b, h) + aoff + m * 2048 + k * 1024); } while (0)
; #define PG8_MMA(ai, bj, At, Bt) do { __builtin_amdgcn_s_setprio(1); _Pragma("unroll") for (int m = 0; m < 4; ++m) _Pragma("unroll") for (int n = 0; n < 2; ++n) _Pragma("unroll") for (int k = 0; k < 2; ++k) \
;         acc[ai][bj][m][n] = __builtin_amdgcn_mfma_f32_16x16x32_bf16(Bt[n][k], At[m][k], acc[ai][bj][m][n], 0, 0, 0); __builtin_amdgcn_s_setprio(0); } while (0)
; #define PG8_WAIT_V(n) asm volatile("s_waitcnt vmcnt(" #n ")" ::: "memory")
; #define PG8_WAIT_L(n) asm volatile("s_waitcnt lgkmcnt(" #n ")" ::: "memory")
; #define PG8_BAR __builtin_amdgcn_s_barrier()
; #define PG8_SCHED __builtin_amdgcn_sched_barrier(0)
; template <class Epi, class Sched, bool ALIGN_EPI = false, bool SP2 = false>
; __device__ __forceinline__ void gemm_phase(PG8_LAS unsigned char* lds, const Gemm g, const Sched& S, const Epi& E) {
;     ...
;         for (int t = 0; t < nt; t += 2) {
;     ...
;             PG8_LDA(At, 1, 1); PG8_STAGE(PG8_SB(1, 0), b3, voffB); PG8_STAGE(PG8_SB(1, 1), b3 + hstep, voffB); PG8_STAGE(PG8_SA(1, 0), a3, voffA);
;             PG8_WAIT_V(8); PG8_WAIT_L(0); PG8_BAR; PG8_MMA(1, 0, At, B0); PG8_MMA(1, 1, At, B1); PG8_BAR; PG8_SCHED;
;     ...
;         if constexpr (ALIGN_EPI) { if (wr == 0) PG8_BAR; }
	s_add_i32 s2, s2, s28
	v_lshl_add_u64 v[218:219], v[218:219], 0, s[0:1]
	s_mov_b32 m0, s2
	ds_read_b128 v[162:165], v234 offset:49152
	ds_read_b128 v[166:169], v234 offset:50176
	ds_read_b128 v[170:173], v234 offset:51200
	ds_read_b128 v[174:177], v234 offset:52224
	ds_read_b128 v[178:181], v234 offset:53248
	ds_read_b128 v[182:185], v234 offset:54272
	ds_read_b128 v[210:213], v234 offset:55296
	ds_read_b128 v[214:217], v234 offset:56320
	global_load_lds_dwordx4 v[218:219], off
	s_add_i32 m0, s2, 0x2000
	s_add_u32 s46, s62, 0x160080
	v_lshl_add_u64 v[218:219], v[236:237], 0, s[0:1]
	s_addc_u32 s47, s63, 0
	s_add_i32 s2, s88, s28
	global_load_lds_dwordx4 v[218:219], off
	v_lshl_add_u64 v[218:219], s[46:47], 0, v[0:1]
	s_mov_b32 m0, s2
	s_nop 0
	global_load_lds_dwordx4 v[218:219], off
	v_lshl_add_u64 v[218:219], s[46:47], 0, v[204:205]
	s_add_i32 m0, s2, 0x2000
	s_nop 0
	global_load_lds_dwordx4 v[218:219], off
	v_lshl_add_u64 v[218:219], v[238:239], 0, s[0:1]
	s_mov_b32 m0, s71
	s_nop 0
	global_load_lds_dwordx4 v[218:219], off
	v_lshl_add_u64 v[218:219], v[240:241], 0, s[0:1]
	s_mov_b32 m0, s76
	s_nop 0
	global_load_lds_dwordx4 v[218:219], off
	s_waitcnt vmcnt(8)
	s_waitcnt lgkmcnt(0)
	s_barrier
	v_mfma_f32_16x16x32_bf16 v[62:65], v[130:133], v[162:165], v[62:65]
	v_mfma_f32_16x16x32_bf16 v[58:61], v[138:141], v[162:165], v[58:61]
	v_mfma_f32_16x16x32_bf16 v[54:57], v[130:133], v[170:173], v[54:57]
	v_mfma_f32_16x16x32_bf16 v[50:53], v[138:141], v[170:173], v[50:53]
	v_mfma_f32_16x16x32_bf16 v[38:41], v[130:133], v[178:181], v[38:41]
	v_mfma_f32_16x16x32_bf16 v[34:37], v[138:141], v[178:181], v[34:37]
	v_mfma_f32_16x16x32_bf16 v[22:25], v[130:133], v[210:213], v[22:25]
	v_mfma_f32_16x16x32_bf16 v[18:21], v[138:141], v[210:213], v[18:21]
	v_mfma_f32_16x16x32_bf16 v[62:65], v[134:137], v[166:169], v[62:65]
	v_mfma_f32_16x16x32_bf16 v[58:61], v[142:145], v[166:169], v[58:61]
	v_mfma_f32_16x16x32_bf16 v[54:57], v[134:137], v[174:177], v[54:57]
	v_mfma_f32_16x16x32_bf16 v[50:53], v[142:145], v[174:177], v[50:53]
	v_mfma_f32_16x16x32_bf16 v[38:41], v[134:137], v[182:185], v[38:41]
	v_mfma_f32_16x16x32_bf16 v[34:37], v[142:145], v[182:185], v[34:37]
	v_mfma_f32_16x16x32_bf16 v[22:25], v[134:137], v[214:217], v[22:25]
	v_mfma_f32_16x16x32_bf16 v[18:21], v[142:145], v[214:217], v[18:21]
	v_mfma_f32_16x16x32_bf16 v[46:49], v[146:149], v[162:165], v[46:49]
	v_mfma_f32_16x16x32_bf16 v[42:45], v[154:157], v[162:165], v[42:45]
	v_mfma_f32_16x16x32_bf16 v[30:33], v[146:149], v[170:173], v[30:33]
	v_mfma_f32_16x16x32_bf16 v[26:29], v[154:157], v[170:173], v[26:29]
	v_mfma_f32_16x16x32_bf16 v[14:17], v[146:149], v[178:181], v[14:17]
	v_mfma_f32_16x16x32_bf16 v[10:13], v[154:157], v[178:181], v[10:13]
	v_mfma_f32_16x16x32_bf16 v[6:9], v[146:149], v[210:213], v[6:9]
	v_mfma_f32_16x16x32_bf16 v[2:5], v[154:157], v[210:213], v[2:5]
	v_mfma_f32_16x16x32_bf16 v[46:49], v[150:153], v[166:169], v[46:49]
	v_mfma_f32_16x16x32_bf16 v[42:45], v[158:161], v[166:169], v[42:45]
	v_mfma_f32_16x16x32_bf16 v[30:33], v[150:153], v[174:177], v[30:33]
	v_mfma_f32_16x16x32_bf16 v[26:29], v[158:161], v[174:177], v[26:29]
	v_mfma_f32_16x16x32_bf16 v[14:17], v[150:153], v[182:185], v[14:17]
	v_mfma_f32_16x16x32_bf16 v[10:13], v[158:161], v[182:185], v[10:13]
	v_mfma_f32_16x16x32_bf16 v[6:9], v[150:153], v[214:217], v[6:9]
	v_mfma_f32_16x16x32_bf16 v[2:5], v[158:161], v[214:217], v[2:5]
	s_barrier
	s_add_u32 s86, s86, 0x100
	s_addc_u32 s87, s87, 0
	s_cmp_ge_i32 s3, s83
	s_mov_b64 s[46:47], s[22:23]
	s_mov_b32 s2, s3
	s_cbranch_scc0 .LBB0_1588
	s_setprio 0
	s_and_b64 vcc, exec, s[54:55]
	s_cbranch_vccz .LBB0_1591
	s_barrier
